# read-once loads also non-temporal in the ffn fix-up, residual epilogues of the down/out projections and the final scale
# baseline (speedup 1.0000x reference)
; __device__ __forceinline__ void phase_ffn_fix(const Params& p, int layer) {
;     ...
;   for (int it = blockIdx.x * NTHR + threadIdx.x; it < nitems; it += gridDim.x * NTHR) {
;     const int f4 = it % (DFF / 4), cj = it / (DFF / 4), j = cj & 1, chunk = cj >> 1;
;     const int f0 = f4 * 4;
;     const int gc = 256 * (f0 >> 7) + (f0 & 127);
;     const int t = chunk * 64 + j;
;     const bool has_prev = ((chunk & 63) != 0);
;     const float* cur = p.ub + (size_t)(chunk * 4) * NUP + gc;
;     const float* prv = p.ub + (size_t)((has_prev ? chunk - 1 : chunk) * 4) * NUP + gc;
;     const float pmask = has_prev ? 1.f : 0.f;
;     const float* r1p = (j == 0) ? prv + (size_t)3 * NUP : cur;
;     const float* r2p = (j == 0) ? prv + (size_t)2 * NUP : prv + (size_t)3 * NUP;
;     const float m1 = (j == 0) ? pmask : 1.f, m2 = pmask;
;     f32x4 g0 = *(const f32x4*)(cur + (size_t)j * NUP), v0 = *(const f32x4*)(cur + (size_t)j * NUP + 128);
;     f32x4 g1 = *(const f32x4*)(r1p) * m1, v1 = *(const f32x4*)(r1p + 128) * m1;
;     f32x4 g2 = *(const f32x4*)(r2p) * m2, v2 = *(const f32x4*)(r2p + 128) * m2;
;     const f32x4 wg0 = *(const f32x4*)(cw + f0), wg1 = *(const f32x4*)(cw + NUP + f0), wg2 = *(const f32x4*)(cw + 2 * NUP + f0);
;     const f32x4 wv0 = *(const f32x4*)(cw + DFF + f0), wv1 = *(const f32x4*)(cw + NUP + DFF + f0), wv2 = *(const f32x4*)(cw + 2 * NUP + DFF + f0);
;     const f32x4 bg = *(const f32x4*)(cb + f0), bv = *(const f32x4*)(cb + DFF + f0);
;     const f32x4 cg_ = bg + g2 * wg0 + g1 * wg1 + g0 * wg2;
;     const f32x4 cv_ = bv + v2 * wv0 + v1 * wv1 + v0 * wv2;
;     const float r0 = cg_[0] / (1.f + __expf(-cg_[0])) * cv_[0], r1 = cg_[1] / (1.f + __expf(-cg_[1])) * cv_[1];
;     const float r2 = cg_[2] / (1.f + __expf(-cg_[2])) * cv_[2], r3 = cg_[3] / (1.f + __expf(-cg_[3])) * cv_[3];
;     *(uint2*)(p.act + (size_t)t * DFF + f0) = make_uint2(pack2(r0, r1), pack2(r2, r3));
;   }
.LBB0_563:
	v_mul_hi_i32 v2, v6, s28
	v_lshrrev_b32_e32 v9, 31, v2
	v_ashrrev_i32_e32 v2, 7, v2
	v_add_u32_e32 v6, s0, v6
	v_add_u32_e32 v2, v2, v9
	v_cmp_lt_i32_e32 vcc, s34, v6
	v_mul_i32_i24_e32 v9, 0x2c0, v2
	v_and_b32_e32 v50, 1, v2
	v_ashrrev_i32_e32 v10, 1, v2
	v_and_b32_e32 v2, 0x7e, v2
	s_or_b64 s[38:39], vcc, s[38:39]
	v_lshlrev_b32_e32 v11, 2, v9
	v_cmp_ne_u32_e32 vcc, 0, v2
	v_lshlrev_b32_e32 v9, 3, v9
	v_lshl_or_b32 v14, v10, 6, v50
	v_lshlrev_b32_e32 v12, 2, v10
	v_subbrev_co_u32_e64 v2, s[4:5], 0, v10, vcc
	v_sub_u32_e32 v10, v7, v11
	v_sub_u32_e32 v9, v8, v9
	v_mul_hi_i32_i24_e32 v13, 0x5800, v12
	v_mul_i32_i24_e32 v12, 0x5800, v12
	v_and_b32_e32 v16, 0x7c, v10
	v_lshl_add_u64 v[42:43], s[56:57], 0, v[12:13]
	v_and_or_b32 v12, v9, s29, v16
	v_lshlrev_b32_e32 v11, 2, v2
	v_ashrrev_i32_e32 v13, 31, v12
	v_mad_i64_i32 v[44:45], s[4:5], v11, s30, v[0:1]
	v_lshlrev_b64 v[46:47], 2, v[12:13]
	v_mul_u32_u24_e32 v15, 0x1600, v50
	v_ashrrev_i32_e32 v11, 31, v10
	v_lshl_add_u64 v[44:45], v[44:45], 0, v[46:47]
	v_cndmask_b32_e64 v66, 0, 1.0, vcc
	v_lshlrev_b32_e32 v2, 2, v15
	v_mad_i64_i32 v[14:15], s[4:5], v14, s31, v[4:5]
	v_lshlrev_b64 v[16:17], 2, v[10:11]
	v_lshl_add_u64 v[42:43], v[42:43], 0, v[46:47]
	v_lshl_add_u64 v[46:47], v[44:45], 0, s[40:41]
	v_lshl_add_u64 v[44:45], v[44:45], 0, s[16:17]
	v_cmp_eq_u32_e32 vcc, 0, v50
	v_lshl_add_u64 v[68:69], v[10:11], 1, v[14:15]
	v_lshl_add_u64 v[10:11], s[50:51], 0, v[16:17]
	v_lshl_add_u64 v[14:15], s[12:13], 0, v[16:17]
	v_lshl_add_u64 v[18:19], s[18:19], 0, v[16:17]
	v_lshl_add_u64 v[22:23], s[20:21], 0, v[16:17]
	v_lshl_add_u64 v[26:27], s[22:23], 0, v[16:17]
	s_waitcnt vmcnt(0)
	v_lshl_add_u64 v[30:31], s[24:25], 0, v[16:17]
	v_lshl_add_u64 v[34:35], s[36:37], 0, v[16:17]
	v_lshl_add_u64 v[38:39], s[26:27], 0, v[16:17]
	v_lshl_add_u64 v[48:49], v[42:43], 0, v[2:3]
	v_cndmask_b32_e32 v55, v43, v47, vcc
	v_cndmask_b32_e32 v54, v42, v46, vcc
	v_cndmask_b32_e32 v63, v47, v45, vcc
	v_cndmask_b32_e32 v62, v46, v44, vcc
	global_load_dwordx4 v[10:13], v[10:11], off nt
	s_nop 0
	global_load_dwordx4 v[14:17], v[14:15], off nt
	s_nop 0
	global_load_dwordx4 v[18:21], v[18:19], off nt
	s_nop 0
	global_load_dwordx4 v[22:25], v[22:23], off nt
	s_nop 0
	global_load_dwordx4 v[26:29], v[26:27], off nt
	s_nop 0
	global_load_dwordx4 v[30:33], v[30:31], off nt
	s_nop 0
	global_load_dwordx4 v[34:37], v[34:35], off nt
	s_nop 0
	global_load_dwordx4 v[38:41], v[38:39], off nt
	s_nop 0
	global_load_dwordx4 v[42:45], v[48:49], off nt
	s_nop 0
	global_load_dwordx4 v[46:49], v[48:49], off offset:512 nt
	s_nop 0
	global_load_dwordx4 v[50:53], v[54:55], off nt
	s_nop 0
	global_load_dwordx4 v[54:57], v[54:55], off offset:512 nt
	s_nop 0
	global_load_dwordx4 v[58:61], v[62:63], off nt
	s_nop 0
	global_load_dwordx4 v[62:65], v[62:63], off offset:512 nt
	v_cndmask_b32_e32 v2, 1.0, v66, vcc
	v_add_u32_e32 v7, s1, v7
	v_add_u32_e32 v8, s3, v8
	s_waitcnt vmcnt(3)
	v_pk_mul_f32 v[50:51], v[50:51], v[2:3] op_sel_hi:[1,0]
	v_pk_mul_f32 v[52:53], v[52:53], v[2:3] op_sel_hi:[1,0]
	s_waitcnt vmcnt(1)
	v_pk_mul_f32 v[58:59], v[58:59], v[66:67] op_sel_hi:[1,0]
	v_pk_mul_f32 v[60:61], v[60:61], v[66:67] op_sel_hi:[1,0]
	v_pk_fma_f32 v[10:11], v[58:59], v[10:11], v[34:35]
	v_pk_fma_f32 v[12:13], v[60:61], v[12:13], v[36:37]
	v_pk_fma_f32 v[10:11], v[50:51], v[14:15], v[10:11]
	v_pk_mul_f32 v[56:57], v[56:57], v[2:3] op_sel_hi:[1,0]
	v_pk_fma_f32 v[10:11], v[42:43], v[18:19], v[10:11]
	v_pk_mul_f32 v[54:55], v[54:55], v[2:3] op_sel_hi:[1,0]
	v_pk_fma_f32 v[12:13], v[52:53], v[16:17], v[12:13]
	v_mul_f32_e32 v2, 0xbfb8aa3b, v10
	v_mul_f32_e32 v9, 0xbfb8aa3b, v11
	v_pk_fma_f32 v[12:13], v[44:45], v[20:21], v[12:13]
	v_exp_f32_e32 v18, v2
	v_exp_f32_e32 v19, v9
	v_mul_f32_e32 v20, 0xbfb8aa3b, v12
	v_mul_f32_e32 v21, 0xbfb8aa3b, v13
	v_exp_f32_e32 v20, v20
	v_exp_f32_e32 v21, v21
	s_waitcnt vmcnt(0)
	v_pk_mul_f32 v[64:65], v[66:67], v[64:65] op_sel_hi:[0,1]
	v_pk_mul_f32 v[62:63], v[66:67], v[62:63] op_sel_hi:[0,1]
	v_pk_add_f32 v[18:19], v[18:19], 1.0 op_sel_hi:[1,0]
	v_pk_fma_f32 v[24:25], v[64:65], v[24:25], v[40:41]
	v_pk_fma_f32 v[22:23], v[62:63], v[22:23], v[38:39]
	v_div_scale_f32 v2, s[4:5], v19, v19, v11
	v_pk_fma_f32 v[14:15], v[56:57], v[28:29], v[24:25]
	v_pk_fma_f32 v[16:17], v[54:55], v[26:27], v[22:23]
	v_pk_add_f32 v[20:21], v[20:21], 1.0 op_sel_hi:[1,0]
	v_div_scale_f32 v22, s[4:5], v18, v18, v10
	v_rcp_f32_e32 v28, v2
	v_div_scale_f32 v24, s[6:7], v21, v21, v13
	v_rcp_f32_e32 v29, v22
	v_pk_fma_f32 v[16:17], v[46:47], v[30:31], v[16:17]
	v_div_scale_f32 v26, s[8:9], v20, v20, v12
	v_rcp_f32_e32 v30, v24
	v_rcp_f32_e32 v31, v26
	v_pk_fma_f32 v[14:15], v[48:49], v[32:33], v[14:15]
	v_fma_f32 v32, -v2, v28, 1.0
	v_div_scale_f32 v9, vcc, v11, v19, v11
	v_fma_f32 v33, -v22, v29, 1.0
	v_fmac_f32_e32 v28, v32, v28
	v_div_scale_f32 v23, s[4:5], v10, v18, v10
	v_fma_f32 v34, -v24, v30, 1.0
	v_fmac_f32_e32 v29, v33, v29
	v_mul_f32_e32 v32, v9, v28
	v_div_scale_f32 v25, s[6:7], v13, v21, v13
	v_fma_f32 v35, -v26, v31, 1.0
	v_fmac_f32_e32 v30, v34, v30
	v_mul_f32_e32 v33, v23, v29
	v_fma_f32 v36, -v2, v32, v9
	v_div_scale_f32 v27, s[8:9], v12, v20, v12
	v_fmac_f32_e32 v31, v35, v31
	v_mul_f32_e32 v34, v25, v30
	v_fma_f32 v37, -v22, v33, v23
	v_fmac_f32_e32 v32, v36, v28
	v_mul_f32_e32 v35, v27, v31
	v_fma_f32 v38, -v24, v34, v25
	v_fmac_f32_e32 v33, v37, v29
	v_fma_f32 v2, -v2, v32, v9
	v_fma_f32 v39, -v26, v35, v27
	v_fmac_f32_e32 v34, v38, v30
	v_fma_f32 v9, -v22, v33, v23
	v_div_fmas_f32 v2, v2, v28, v32
	s_mov_b64 vcc, s[4:5]
	v_fmac_f32_e32 v35, v39, v31
	v_fma_f32 v22, -v24, v34, v25
	v_div_fixup_f32 v11, v2, v19, v11
	v_div_fmas_f32 v2, v9, v29, v33
	s_mov_b64 vcc, s[6:7]
	v_fma_f32 v23, -v26, v35, v27
	v_div_fixup_f32 v10, v2, v18, v10
	v_div_fmas_f32 v2, v22, v30, v34
	s_mov_b64 vcc, s[8:9]
	v_div_fixup_f32 v13, v2, v21, v13
	v_div_fmas_f32 v2, v23, v31, v35
	v_div_fixup_f32 v12, v2, v20, v12
	v_pk_mul_f32 v[10:11], v[16:17], v[10:11]
	v_pk_mul_f32 v[12:13], v[14:15], v[12:13]
	v_cvt_pk_bf16_f32 v10, v10, v11
	v_cvt_pk_bf16_f32 v11, v12, v13
	global_store_dwordx2 v[68:69], v[10:11], off
	s_andn2_b64 exec, exec, s[38:39]
	s_cbranch_execnz .LBB0_563

; #define PG8_STAGE(bufoff, gbase, voff) do { _Pragma("unroll") for (int _i = 0; _i < 2; ++_i) \
;     __builtin_amdgcn_global_load_lds((const unsigned*)((const char*)(gbase) + (voff)[_i]), (LAS unsigned*)(lds + (bufoff) + ldsw + _i * 8192), 16, 0, 0); } while (0)
; #define PG8_LDB(dst, b, h) do { \
;     PG8_DSR(dst[0][0], baddr, ((b) * 2 + (h)) * PG_HTB + 0 * 2048 + 0);    PG8_DSR(dst[0][1], baddr, ((b) * 2 + (h)) * PG_HTB + 0 * 2048 + 1024); \
;     PG8_DSR(dst[1][0], baddr, ((b) * 2 + (h)) * PG_HTB + 1 * 2048 + 0);    PG8_DSR(dst[1][1], baddr, ((b) * 2 + (h)) * PG_HTB + 1 * 2048 + 1024); } while (0)
; #define PG8_MMA(ai, bj, At, Bt) do { __builtin_amdgcn_s_setprio(1); _Pragma("unroll") for (int m = 0; m < 4; ++m) _Pragma("unroll") for (int n = 0; n < 2; ++n) _Pragma("unroll") for (int k = 0; k < 2; ++k) \
;     acc[ai][bj][m][n] = __builtin_amdgcn_mfma_f32_16x16x32_bf16(Bt[n][k], At[m][k], acc[ai][bj][m][n], 0, 0, 0); __builtin_amdgcn_s_setprio(0); } while (0)
; #define PG8_WAIT_V(n) asm volatile("s_waitcnt vmcnt(" #n ")" ::: "memory")
; #define PG8_WAIT_L(n) asm volatile("s_waitcnt lgkmcnt(" #n ")" ::: "memory")
; #define PG8_WAIT_L0 asm volatile("s_waitcnt lgkmcnt(0)" \
;     : "+v"(At[0][0]), "+v"(At[0][1]), "+v"(At[1][0]), "+v"(At[1][1]), "+v"(At[2][0]), "+v"(At[2][1]), "+v"(At[3][0]), "+v"(At[3][1]), \
;       "+v"(B0[0][0]), "+v"(B0[0][1]), "+v"(B0[1][0]), "+v"(B0[1][1]), "+v"(B1[0][0]), "+v"(B1[0][1]), "+v"(B1[1][0]), "+v"(B1[1][1]) :: "memory")
; #define PG8_BAR __builtin_amdgcn_s_barrier()
; #define PG8_SCHED __builtin_amdgcn_sched_barrier(0)
; template <class Epi>
; __device__ __forceinline__ void gemm_phase(LAS unsigned char* lds, const Gemm g, const StaticOrder& S, const Epi& E) {
;     ...
;       PG8_LDB(B0, 0, 0); PG8_SCHED; PG8_LDA(At, 0, 0); PG8_STAGE(PG8_SA(1, 1), a1 + hstep, voffA);
;       PG8_WAIT_L(8); PG8_BAR; PG8_WAIT_L0; PG8_MMA(0, 0, At, B0); PG8_BAR; PG8_SCHED;
;       PG8_LDB(B1, 0, 1); PG8_STAGE(PG8_SB(0, 0), b2, voffA);
;       PG8_BAR; PG8_WAIT_L0; PG8_MMA(0, 1, At, B1); PG8_BAR;
;       PG8_LDA(At, 0, 1); PG8_STAGE(PG8_SA(0, 0), a2, voffA);
;       PG8_BAR; PG8_WAIT_L0; PG8_MMA(1, 0, At, B0); PG8_BAR; PG8_SCHED;
;       PG8_STAGE(PG8_SB(0, 1), b2 + hstep, voffA);
;       PG8_WAIT_V(6); PG8_BAR; PG8_MMA(1, 1, At, B1); PG8_BAR;
.LBB0_629:
	ds_read_b128 v[156:159], v200 offset:0
	ds_read_b128 v[160:163], v200 offset:0x400
	ds_read_b128 v[164:167], v200 offset:0x800
	s_add_u32 s20, s18, 0xfff50080
	ds_read_b128 v[168:171], v200 offset:0xc00
	s_addc_u32 s21, s19, -1
	s_cmp_eq_u32 s35, 40
	s_cselect_b32 s23, s9, s21
	s_cselect_b32 s22, s8, s20
	ds_read_b128 v[172:175], v199 offset:0
	ds_read_b128 v[176:179], v199 offset:0x400
	ds_read_b128 v[180:183], v199 offset:0x800
	ds_read_b128 v[184:187], v199 offset:0xc00
	ds_read_b128 v[188:191], v199 offset:0x1000
	ds_read_b128 v[194:197], v199 offset:0x1400
	ds_read_b128 v[204:207], v199 offset:0x1800
	s_mov_b32 m0, s50
	ds_read_b128 v[208:211], v199 offset:0x1c00
	v_lshl_add_u64 v[212:213], s[18:19], 0, v[148:149]
	global_load_lds_dwordx4 v[212:213], off
	v_lshl_add_u64 v[212:213], s[18:19], 0, v[150:151]
	s_mov_b32 m0, s51
	s_cselect_b32 s21, s11, s34
	global_load_lds_dwordx4 v[212:213], off
	s_waitcnt lgkmcnt(8)
	s_barrier
	s_waitcnt lgkmcnt(0)
	s_cselect_b32 s20, s10, s63
	s_setprio 1
	v_mfma_f32_16x16x32_bf16 v[0:3], v[156:159], v[172:175], v[140:143]
	v_mfma_f32_16x16x32_bf16 v[4:7], v[164:167], v[172:175], v[136:139]
	v_mfma_f32_16x16x32_bf16 v[8:11], v[156:159], v[180:183], v[124:127]
	v_mfma_f32_16x16x32_bf16 v[12:15], v[164:167], v[180:183], v[120:123]
	v_mfma_f32_16x16x32_bf16 v[108:111], v[156:159], v[188:191], v[108:111]
	v_mfma_f32_16x16x32_bf16 v[104:107], v[164:167], v[188:191], v[104:107]
	v_mfma_f32_16x16x32_bf16 v[92:95], v[156:159], v[204:207], v[92:95]
	v_mfma_f32_16x16x32_bf16 v[88:91], v[164:167], v[204:207], v[88:91]
	v_mfma_f32_16x16x32_bf16 v[0:3], v[160:163], v[176:179], v[0:3]
	v_mfma_f32_16x16x32_bf16 v[4:7], v[168:171], v[176:179], v[4:7]
	v_mfma_f32_16x16x32_bf16 v[8:11], v[160:163], v[184:187], v[8:11]
	v_mfma_f32_16x16x32_bf16 v[12:15], v[168:171], v[184:187], v[12:15]
	v_mfma_f32_16x16x32_bf16 v[108:111], v[160:163], v[194:197], v[108:111]
	v_mfma_f32_16x16x32_bf16 v[104:107], v[168:171], v[194:197], v[104:107]
	v_mfma_f32_16x16x32_bf16 v[92:95], v[160:163], v[208:211], v[92:95]
	v_mfma_f32_16x16x32_bf16 v[88:91], v[168:171], v[208:211], v[88:91]
	s_setprio 0
	s_barrier
	ds_read_b128 v[120:123], v200 offset:0x4000
	ds_read_b128 v[124:127], v200 offset:0x4400
	ds_read_b128 v[136:139], v200 offset:0x4800
	s_mov_b32 m0, s24
	ds_read_b128 v[140:143], v200 offset:0x4c00
	v_lshl_add_u64 v[212:213], s[20:21], 0, v[144:145]
	global_load_lds_dwordx4 v[212:213], off
	v_lshl_add_u64 v[214:215], s[20:21], 0, v[146:147]
	s_mov_b32 m0, s25
	s_nop 0
	global_load_lds_dwordx4 v[214:215], off
	s_barrier
	s_waitcnt lgkmcnt(0)
	s_setprio 1
	v_mfma_f32_16x16x32_bf16 v[132:135], v[120:123], v[172:175], v[132:135]
	v_mfma_f32_16x16x32_bf16 v[128:131], v[136:139], v[172:175], v[128:131]
	v_mfma_f32_16x16x32_bf16 v[116:119], v[120:123], v[180:183], v[116:119]
	v_mfma_f32_16x16x32_bf16 v[112:115], v[136:139], v[180:183], v[112:115]
	v_mfma_f32_16x16x32_bf16 v[100:103], v[120:123], v[188:191], v[100:103]
	v_mfma_f32_16x16x32_bf16 v[96:99], v[136:139], v[188:191], v[96:99]
	v_mfma_f32_16x16x32_bf16 v[84:87], v[120:123], v[204:207], v[84:87]
	v_mfma_f32_16x16x32_bf16 v[80:83], v[136:139], v[204:207], v[80:83]
	v_mfma_f32_16x16x32_bf16 v[132:135], v[124:127], v[176:179], v[132:135]
	v_mfma_f32_16x16x32_bf16 v[128:131], v[140:143], v[176:179], v[128:131]
	v_mfma_f32_16x16x32_bf16 v[116:119], v[124:127], v[184:187], v[116:119]
	v_mfma_f32_16x16x32_bf16 v[112:115], v[140:143], v[184:187], v[112:115]
	v_mfma_f32_16x16x32_bf16 v[100:103], v[124:127], v[194:197], v[100:103]
	v_mfma_f32_16x16x32_bf16 v[96:99], v[140:143], v[194:197], v[96:99]
	v_mfma_f32_16x16x32_bf16 v[84:87], v[124:127], v[208:211], v[84:87]
	v_mfma_f32_16x16x32_bf16 v[80:83], v[140:143], v[208:211], v[80:83]
	s_setprio 0
	s_barrier
	ds_read_b128 v[172:175], v199 offset:0x4000
	ds_read_b128 v[176:179], v199 offset:0x4400
	ds_read_b128 v[180:183], v199 offset:0x4800
	ds_read_b128 v[184:187], v199 offset:0x4c00
	ds_read_b128 v[188:191], v199 offset:0x5000
	ds_read_b128 v[194:197], v199 offset:0x5400
	ds_read_b128 v[204:207], v199 offset:0x5800
	s_mov_b32 m0, s3
	ds_read_b128 v[208:211], v199 offset:0x5c00
	v_lshl_add_u64 v[216:217], s[22:23], 0, v[144:145]
	global_load_lds_dwordx4 v[216:217], off
	v_lshl_add_u64 v[218:219], s[22:23], 0, v[146:147]
	s_mov_b32 m0, s26
	s_nop 0
	global_load_lds_dwordx4 v[218:219], off
	s_barrier
	s_waitcnt lgkmcnt(0)
	s_setprio 1
	v_mfma_f32_16x16x32_bf16 v[76:79], v[156:159], v[172:175], v[76:79]
	v_mfma_f32_16x16x32_bf16 v[72:75], v[164:167], v[172:175], v[72:75]
	v_mfma_f32_16x16x32_bf16 v[60:63], v[156:159], v[180:183], v[60:63]
	v_mfma_f32_16x16x32_bf16 v[56:59], v[164:167], v[180:183], v[56:59]
	v_mfma_f32_16x16x32_bf16 v[44:47], v[156:159], v[188:191], v[44:47]
	v_mfma_f32_16x16x32_bf16 v[40:43], v[164:167], v[188:191], v[40:43]
	v_mfma_f32_16x16x32_bf16 v[28:31], v[156:159], v[204:207], v[28:31]
	v_mfma_f32_16x16x32_bf16 v[24:27], v[164:167], v[204:207], v[24:27]
	v_mfma_f32_16x16x32_bf16 v[76:79], v[160:163], v[176:179], v[76:79]
	v_mfma_f32_16x16x32_bf16 v[72:75], v[168:171], v[176:179], v[72:75]
	v_mfma_f32_16x16x32_bf16 v[60:63], v[160:163], v[184:187], v[60:63]
	v_mfma_f32_16x16x32_bf16 v[56:59], v[168:171], v[184:187], v[56:59]
	v_mfma_f32_16x16x32_bf16 v[44:47], v[160:163], v[194:197], v[44:47]
	v_mfma_f32_16x16x32_bf16 v[40:43], v[168:171], v[194:197], v[40:43]
	v_mfma_f32_16x16x32_bf16 v[28:31], v[160:163], v[208:211], v[28:31]
	v_mfma_f32_16x16x32_bf16 v[24:27], v[168:171], v[208:211], v[24:27]
	s_setprio 0
	s_barrier
; #define PG8_STAGE(bufoff, gbase, voff) do { _Pragma("unroll") for (int _i = 0; _i < 2; ++_i) \
;     __builtin_amdgcn_global_load_lds((const unsigned*)((const char*)(gbase) + (voff)[_i]), (LAS unsigned*)(lds + (bufoff) + ldsw + _i * 8192), 16, 0, 0); } while (0)
; #define PG8_LDB(dst, b, h) do { \
;     PG8_DSR(dst[0][0], baddr, ((b) * 2 + (h)) * PG_HTB + 0 * 2048 + 0);    PG8_DSR(dst[0][1], baddr, ((b) * 2 + (h)) * PG_HTB + 0 * 2048 + 1024); \
;     PG8_DSR(dst[1][0], baddr, ((b) * 2 + (h)) * PG_HTB + 1 * 2048 + 0);    PG8_DSR(dst[1][1], baddr, ((b) * 2 + (h)) * PG_HTB + 1 * 2048 + 1024); } while (0)
; #define PG8_MMA(ai, bj, At, Bt) do { __builtin_amdgcn_s_setprio(1); _Pragma("unroll") for (int m = 0; m < 4; ++m) _Pragma("unroll") for (int n = 0; n < 2; ++n) _Pragma("unroll") for (int k = 0; k < 2; ++k) \
;     acc[ai][bj][m][n] = __builtin_amdgcn_mfma_f32_16x16x32_bf16(Bt[n][k], At[m][k], acc[ai][bj][m][n], 0, 0, 0); __builtin_amdgcn_s_setprio(0); } while (0)
; #define PG8_WAIT_V(n) asm volatile("s_waitcnt vmcnt(" #n ")" ::: "memory")
; #define PG8_WAIT_L(n) asm volatile("s_waitcnt lgkmcnt(" #n ")" ::: "memory")
; #define PG8_WAIT_L0 asm volatile("s_waitcnt lgkmcnt(0)" \
;     : "+v"(At[0][0]), "+v"(At[0][1]), "+v"(At[1][0]), "+v"(At[1][1]), "+v"(At[2][0]), "+v"(At[2][1]), "+v"(At[3][0]), "+v"(At[3][1]), \
;       "+v"(B0[0][0]), "+v"(B0[0][1]), "+v"(B0[1][0]), "+v"(B0[1][1]), "+v"(B1[0][0]), "+v"(B1[0][1]), "+v"(B1[1][0]), "+v"(B1[1][1]) :: "memory")
; #define PG8_BAR __builtin_amdgcn_s_barrier()
; #define PG8_SCHED __builtin_amdgcn_sched_barrier(0)
; template <class Epi>
; __device__ __forceinline__ void gemm_phase(LAS unsigned char* lds, const Gemm g, const StaticOrder& S, const Epi& E) {
;     ...
;       PG8_WAIT_V(6); PG8_BAR; PG8_MMA(1, 1, At, B1); PG8_BAR;
;       PG8_LDB(B0, 1, 0); PG8_SCHED; PG8_LDA(At, 1, 0); PG8_STAGE(PG8_SA(0, 1), a2 + hstep, voffA);
;       PG8_WAIT_L(8); PG8_BAR; PG8_WAIT_L0; PG8_MMA(0, 0, At, B0); PG8_BAR; PG8_SCHED;
;       PG8_LDB(B1, 1, 1); PG8_STAGE(PG8_SB(1, 0), b3, voffA);
;       PG8_BAR; PG8_WAIT_L0; PG8_MMA(0, 1, At, B1); PG8_BAR;
;       PG8_LDA(At, 1, 1); PG8_STAGE(PG8_SA(1, 0), a3, voffA);
;       PG8_BAR; PG8_WAIT_L0; PG8_MMA(1, 0, At, B0); PG8_BAR; PG8_SCHED;
;       PG8_STAGE(PG8_SB(1, 1), b3 + hstep, voffA);
	s_add_u32 s36, s20, 0xb0000
	s_addc_u32 s37, s21, 0
	s_mov_b32 m0, s27
	v_lshl_add_u64 v[156:157], s[36:37], 0, v[144:145]
	global_load_lds_dwordx4 v[156:157], off
	v_lshl_add_u64 v[156:157], s[36:37], 0, v[146:147]
	s_mov_b32 m0, s28
	s_nop 0
	global_load_lds_dwordx4 v[156:157], off
	s_waitcnt vmcnt(6)
	s_barrier
	s_setprio 1
	v_mfma_f32_16x16x32_bf16 v[68:71], v[120:123], v[172:175], v[68:71]
	v_mfma_f32_16x16x32_bf16 v[64:67], v[136:139], v[172:175], v[64:67]
	v_mfma_f32_16x16x32_bf16 v[52:55], v[120:123], v[180:183], v[52:55]
	v_mfma_f32_16x16x32_bf16 v[48:51], v[136:139], v[180:183], v[48:51]
	v_mfma_f32_16x16x32_bf16 v[36:39], v[120:123], v[188:191], v[36:39]
	v_mfma_f32_16x16x32_bf16 v[32:35], v[136:139], v[188:191], v[32:35]
	v_mfma_f32_16x16x32_bf16 v[20:23], v[120:123], v[204:207], v[20:23]
	v_mfma_f32_16x16x32_bf16 v[16:19], v[136:139], v[204:207], v[16:19]
	v_mfma_f32_16x16x32_bf16 v[68:71], v[124:127], v[176:179], v[68:71]
	v_mfma_f32_16x16x32_bf16 v[64:67], v[140:143], v[176:179], v[64:67]
	v_mfma_f32_16x16x32_bf16 v[52:55], v[124:127], v[184:187], v[52:55]
	v_mfma_f32_16x16x32_bf16 v[48:51], v[140:143], v[184:187], v[48:51]
	v_mfma_f32_16x16x32_bf16 v[36:39], v[124:127], v[194:197], v[36:39]
	v_mfma_f32_16x16x32_bf16 v[32:35], v[140:143], v[194:197], v[32:35]
	v_mfma_f32_16x16x32_bf16 v[20:23], v[124:127], v[208:211], v[20:23]
	v_mfma_f32_16x16x32_bf16 v[16:19], v[140:143], v[208:211], v[16:19]
	s_setprio 0
	s_barrier
	ds_read_b128 v[156:159], v200 offset:0x8000
	ds_read_b128 v[160:163], v200 offset:0x8400
	ds_read_b128 v[164:167], v200 offset:0x8800
	ds_read_b128 v[168:171], v200 offset:0x8c00
	ds_read_b128 v[172:175], v199 offset:0x8000
	ds_read_b128 v[176:179], v199 offset:0x8400
	ds_read_b128 v[180:183], v199 offset:0x8800
	ds_read_b128 v[184:187], v199 offset:0x8c00
	ds_read_b128 v[188:191], v199 offset:0x9000
	ds_read_b128 v[194:197], v199 offset:0x9400
	s_add_u32 s22, s22, 0xb0000
	ds_read_b128 v[204:207], v199 offset:0x9800
	s_addc_u32 s23, s23, 0
	s_mov_b32 m0, s29
	ds_read_b128 v[208:211], v199 offset:0x9c00
	v_lshl_add_u64 v[220:221], s[22:23], 0, v[144:145]
	global_load_lds_dwordx4 v[220:221], off
	v_lshl_add_u64 v[220:221], s[22:23], 0, v[146:147]
	s_mov_b32 m0, s30
	s_nop 0
	global_load_lds_dwordx4 v[220:221], off
	s_waitcnt lgkmcnt(8)
	s_barrier
	s_waitcnt lgkmcnt(0)
	s_setprio 1
	v_mfma_f32_16x16x32_bf16 v[0:3], v[156:159], v[172:175], v[0:3]
	v_mfma_f32_16x16x32_bf16 v[140:143], v[160:163], v[176:179], v[0:3]
	v_mfma_f32_16x16x32_bf16 v[0:3], v[164:167], v[172:175], v[4:7]
	v_mfma_f32_16x16x32_bf16 v[136:139], v[168:171], v[176:179], v[0:3]
	v_mfma_f32_16x16x32_bf16 v[0:3], v[156:159], v[180:183], v[8:11]
	v_mfma_f32_16x16x32_bf16 v[124:127], v[160:163], v[184:187], v[0:3]
	v_mfma_f32_16x16x32_bf16 v[0:3], v[164:167], v[180:183], v[12:15]
	v_mfma_f32_16x16x32_bf16 v[120:123], v[168:171], v[184:187], v[0:3]
	v_mfma_f32_16x16x32_bf16 v[0:3], v[156:159], v[188:191], v[108:111]
	v_mfma_f32_16x16x32_bf16 v[108:111], v[160:163], v[194:197], v[0:3]
	v_mfma_f32_16x16x32_bf16 v[0:3], v[164:167], v[188:191], v[104:107]
	v_mfma_f32_16x16x32_bf16 v[104:107], v[168:171], v[194:197], v[0:3]
	v_mfma_f32_16x16x32_bf16 v[0:3], v[156:159], v[204:207], v[92:95]
	v_mfma_f32_16x16x32_bf16 v[92:95], v[160:163], v[208:211], v[0:3]
	v_mfma_f32_16x16x32_bf16 v[0:3], v[164:167], v[204:207], v[88:91]
	v_mfma_f32_16x16x32_bf16 v[88:91], v[168:171], v[208:211], v[0:3]
	s_setprio 0
	s_barrier
	ds_read_b128 v[12:15], v200 offset:0xc000
	ds_read_b128 v[8:11], v200 offset:0xc400
	ds_read_b128 v[4:7], v200 offset:0xc800
	s_mov_b32 m0, s31
	ds_read_b128 v[0:3], v200 offset:0xcc00
	v_lshl_add_u64 v[212:213], v[212:213], 0, s[16:17]
	global_load_lds_dwordx4 v[212:213], off
	v_lshl_add_u64 v[212:213], v[214:215], 0, s[16:17]
	s_mov_b32 m0, s38
	s_nop 0
	global_load_lds_dwordx4 v[212:213], off
	s_barrier
	s_waitcnt lgkmcnt(0)
	s_setprio 1
	v_mfma_f32_16x16x32_bf16 v[132:135], v[12:15], v[172:175], v[132:135]
	v_mfma_f32_16x16x32_bf16 v[128:131], v[4:7], v[172:175], v[128:131]
	v_mfma_f32_16x16x32_bf16 v[116:119], v[12:15], v[180:183], v[116:119]
	v_mfma_f32_16x16x32_bf16 v[112:115], v[4:7], v[180:183], v[112:115]
	v_mfma_f32_16x16x32_bf16 v[100:103], v[12:15], v[188:191], v[100:103]
	v_mfma_f32_16x16x32_bf16 v[96:99], v[4:7], v[188:191], v[96:99]
	v_mfma_f32_16x16x32_bf16 v[84:87], v[12:15], v[204:207], v[84:87]
	v_mfma_f32_16x16x32_bf16 v[80:83], v[4:7], v[204:207], v[80:83]
	v_mfma_f32_16x16x32_bf16 v[132:135], v[8:11], v[176:179], v[132:135]
	v_mfma_f32_16x16x32_bf16 v[128:131], v[0:3], v[176:179], v[128:131]
	v_mfma_f32_16x16x32_bf16 v[116:119], v[8:11], v[184:187], v[116:119]
	v_mfma_f32_16x16x32_bf16 v[112:115], v[0:3], v[184:187], v[112:115]
	v_mfma_f32_16x16x32_bf16 v[100:103], v[8:11], v[194:197], v[100:103]
	v_mfma_f32_16x16x32_bf16 v[96:99], v[0:3], v[194:197], v[96:99]
	v_mfma_f32_16x16x32_bf16 v[84:87], v[8:11], v[208:211], v[84:87]
	v_mfma_f32_16x16x32_bf16 v[80:83], v[0:3], v[208:211], v[80:83]
	s_setprio 0
	s_barrier
	ds_read_b128 v[172:175], v199 offset:0xc000
	ds_read_b128 v[176:179], v199 offset:0xc400
	ds_read_b128 v[180:183], v199 offset:0xc800
	ds_read_b128 v[184:187], v199 offset:0xcc00
	ds_read_b128 v[188:191], v199 offset:0xd000
	ds_read_b128 v[194:197], v199 offset:0xd400
	ds_read_b128 v[204:207], v199 offset:0xd800
	s_mov_b32 m0, s39
	ds_read_b128 v[208:211], v199 offset:0xdc00
	v_lshl_add_u64 v[212:213], v[216:217], 0, s[16:17]
	global_load_lds_dwordx4 v[212:213], off
	v_lshl_add_u64 v[212:213], v[218:219], 0, s[16:17]
	s_mov_b32 m0, s40
	s_nop 0
	global_load_lds_dwordx4 v[212:213], off
	s_barrier
; #define PG8_STAGE(bufoff, gbase, voff) do { _Pragma("unroll") for (int _i = 0; _i < 2; ++_i) \
;     __builtin_amdgcn_global_load_lds((const unsigned*)((const char*)(gbase) + (voff)[_i]), (LAS unsigned*)(lds + (bufoff) + ldsw + _i * 8192), 16, 0, 0); } while (0)
; #define PG8_MMA(ai, bj, At, Bt) do { __builtin_amdgcn_s_setprio(1); _Pragma("unroll") for (int m = 0; m < 4; ++m) _Pragma("unroll") for (int n = 0; n < 2; ++n) _Pragma("unroll") for (int k = 0; k < 2; ++k) \
;     acc[ai][bj][m][n] = __builtin_amdgcn_mfma_f32_16x16x32_bf16(Bt[n][k], At[m][k], acc[ai][bj][m][n], 0, 0, 0); __builtin_amdgcn_s_setprio(0); } while (0)
; #define PG8_WAIT_V(n) asm volatile("s_waitcnt vmcnt(" #n ")" ::: "memory")
; #define PG8_BAR __builtin_amdgcn_s_barrier()
; template <class Epi>
; __device__ __forceinline__ void gemm_phase(LAS unsigned char* lds, const Gemm g, const StaticOrder& S, const Epi& E) {
;     ...
;       PG8_STAGE(PG8_SB(1, 1), b3 + hstep, voffA);
;       PG8_WAIT_V(6); PG8_BAR; PG8_MMA(1, 1, At, B1); PG8_BAR;
	s_waitcnt lgkmcnt(0)
	s_setprio 1
	v_mfma_f32_16x16x32_bf16 v[76:79], v[156:159], v[172:175], v[76:79]
	v_mfma_f32_16x16x32_bf16 v[72:75], v[164:167], v[172:175], v[72:75]
	v_mfma_f32_16x16x32_bf16 v[60:63], v[156:159], v[180:183], v[60:63]
	v_mfma_f32_16x16x32_bf16 v[56:59], v[164:167], v[180:183], v[56:59]
	v_mfma_f32_16x16x32_bf16 v[44:47], v[156:159], v[188:191], v[44:47]
	v_mfma_f32_16x16x32_bf16 v[40:43], v[164:167], v[188:191], v[40:43]
	v_mfma_f32_16x16x32_bf16 v[28:31], v[156:159], v[204:207], v[28:31]
	v_mfma_f32_16x16x32_bf16 v[24:27], v[164:167], v[204:207], v[24:27]
	v_mfma_f32_16x16x32_bf16 v[76:79], v[160:163], v[176:179], v[76:79]
	v_mfma_f32_16x16x32_bf16 v[72:75], v[168:171], v[176:179], v[72:75]
	v_mfma_f32_16x16x32_bf16 v[60:63], v[160:163], v[184:187], v[60:63]
	v_mfma_f32_16x16x32_bf16 v[56:59], v[168:171], v[184:187], v[56:59]
	v_mfma_f32_16x16x32_bf16 v[44:47], v[160:163], v[194:197], v[44:47]
	v_mfma_f32_16x16x32_bf16 v[40:43], v[168:171], v[194:197], v[40:43]
	v_mfma_f32_16x16x32_bf16 v[28:31], v[160:163], v[208:211], v[28:31]
	v_mfma_f32_16x16x32_bf16 v[24:27], v[168:171], v[208:211], v[24:27]
	s_setprio 0
	s_barrier
	s_add_u32 s20, s20, 0xb0080
	s_addc_u32 s21, s21, 0
	s_mov_b32 m0, s41
	v_lshl_add_u64 v[156:157], s[20:21], 0, v[144:145]
	global_load_lds_dwordx4 v[156:157], off
	v_lshl_add_u64 v[156:157], s[20:21], 0, v[146:147]
	s_mov_b32 m0, s46
	s_nop 0
	global_load_lds_dwordx4 v[156:157], off
	s_waitcnt vmcnt(6)
	s_barrier
	s_setprio 1
	v_mfma_f32_16x16x32_bf16 v[68:71], v[12:15], v[172:175], v[68:71]
	v_mfma_f32_16x16x32_bf16 v[64:67], v[4:7], v[172:175], v[64:67]
	v_mfma_f32_16x16x32_bf16 v[52:55], v[12:15], v[180:183], v[52:55]
	v_mfma_f32_16x16x32_bf16 v[48:51], v[4:7], v[180:183], v[48:51]
	v_mfma_f32_16x16x32_bf16 v[36:39], v[12:15], v[188:191], v[36:39]
	v_mfma_f32_16x16x32_bf16 v[32:35], v[4:7], v[188:191], v[32:35]
	v_mfma_f32_16x16x32_bf16 v[20:23], v[12:15], v[204:207], v[20:23]
	v_mfma_f32_16x16x32_bf16 v[16:19], v[4:7], v[204:207], v[16:19]
	v_mfma_f32_16x16x32_bf16 v[68:71], v[8:11], v[176:179], v[68:71]
	v_mfma_f32_16x16x32_bf16 v[64:67], v[0:3], v[176:179], v[64:67]
	v_mfma_f32_16x16x32_bf16 v[52:55], v[8:11], v[184:187], v[52:55]
	v_mfma_f32_16x16x32_bf16 v[48:51], v[0:3], v[184:187], v[48:51]
	v_mfma_f32_16x16x32_bf16 v[36:39], v[8:11], v[194:197], v[36:39]
	v_mfma_f32_16x16x32_bf16 v[32:35], v[0:3], v[194:197], v[32:35]
	v_mfma_f32_16x16x32_bf16 v[20:23], v[8:11], v[208:211], v[20:23]
	v_mfma_f32_16x16x32_bf16 v[16:19], v[0:3], v[208:211], v[16:19]
	s_setprio 0
	s_add_i32 s35, s35, 2
	s_add_u32 s18, s18, 0x100
	s_addc_u32 s19, s19, 0
	s_add_u32 s63, s63, 0x100
	s_addc_u32 s34, s34, 0
	s_cmp_gt_u32 s35, 41
	s_barrier
	s_cbranch_scc0 .LBB0_629
; __device__ __forceinline__ uint2 pack4(f32x4 v) { return make_uint2(pack2(v[0], v[1]), pack2(v[2], v[3])); }
;   __device__ __forceinline__ void operator()(const AccT& acc, const Unit& u, int wr, int wc, int fr, int fq) const {
;     ...
;     for (int ai = 0; ai < 2; ++ai) {
;       f32x4 rv[4][2][2];
; #pragma unroll
;       for (int m = 0; m < 4; ++m) {
;         const size_t ro = (size_t)EPI_ROW(u, ai, m) * DM;
; #pragma unroll
;         for (int bj = 0; bj < 2; ++bj)
; #pragma unroll
;           for (int n = 0; n < 2; ++n) {
;             if (RF32) rv[m][bj][n] = *(const f32x4*)(resid32 + ro + EPI_COL(u, bj, n));
;             else {
;               const uint2 pk = *(const uint2*)(xb + ro + EPI_COL(u, bj, n));
;               rv[m][bj][n] = (f32x4){__uint_as_float(pk.x << 16), __uint_as_float(pk.x & 0xffff0000u), __uint_as_float(pk.y << 16), __uint_as_float(pk.y & 0xffff0000u)};
;             }
;           }
;       }
; #pragma unroll
;       for (int m = 0; m < 4; ++m) {
;         const int row = EPI_ROW(u, ai, m);
;         const size_t ro = (size_t)row * DM;
;         float ss = 0.f;
; #pragma unroll
;         for (int bj = 0; bj < 2; ++bj)
; #pragma unroll
;           for (int n = 0; n < 2; ++n) {
;             const f32x4 x = rv[m][bj][n] + acc[ai][bj][m][n];
;             ss += x[0] * x[0] + x[1] * x[1] + x[2] * x[2] + x[3] * x[3];
;             *(uint2*)(xb + ro + EPI_COL(u, bj, n)) = pack4(x);
;           }
;         ss += __shfl_xor(ss, 16);
;         ss += __shfl_xor(ss, 32);
;         if (fq == 0) atomicAdd(rowss + row, (unsigned long long)(ss * SS_FIX + 0.5f));
	v_lshl_add_u32 v156, s62, 8, v198
	v_lshl_or_b32 v158, s61, 8, v201
	v_ashrrev_i32_e32 v157, 31, v156
	v_lshlrev_b64 v[160:161], 11, v[156:157]
	v_ashrrev_i32_e32 v159, 31, v158
	v_lshl_add_u64 v[160:161], s[54:55], 0, v[160:161]
	v_lshlrev_b64 v[158:159], 1, v[158:159]
	v_lshl_add_u64 v[206:207], v[160:161], 0, v[158:159]
	global_load_dwordx2 v[208:209], v[206:207], off nt
	global_load_dwordx2 v[210:211], v[206:207], off offset:32 nt
	global_load_dwordx2 v[212:213], v[206:207], off offset:256 nt
	global_load_dwordx2 v[214:215], v[206:207], off offset:288 nt
	v_or_b32_e32 v176, 16, v156
	v_or_b32_e32 v164, 32, v156
	v_or_b32_e32 v160, 48, v156
	v_ashrrev_i32_e32 v177, 31, v176
	v_ashrrev_i32_e32 v165, 31, v164
	v_ashrrev_i32_e32 v161, 31, v160
	v_lshlrev_b64 v[162:163], 11, v[176:177]
	v_lshlrev_b64 v[166:167], 11, v[164:165]
	v_lshlrev_b64 v[168:169], 11, v[160:161]
	v_lshl_add_u64 v[162:163], s[54:55], 0, v[162:163]
	v_lshl_add_u64 v[166:167], s[54:55], 0, v[166:167]
	v_lshl_add_u64 v[168:169], s[54:55], 0, v[168:169]
	v_lshl_add_u64 v[186:187], v[162:163], 0, v[158:159]
	v_lshl_add_u64 v[174:175], v[166:167], 0, v[158:159]
	v_lshl_add_u64 v[162:163], v[168:169], 0, v[158:159]
	global_load_dwordx2 v[196:197], v[186:187], off nt
	global_load_dwordx2 v[194:195], v[186:187], off offset:32 nt
	global_load_dwordx2 v[190:191], v[186:187], off offset:256 nt
	global_load_dwordx2 v[188:189], v[186:187], off offset:288 nt
	global_load_dwordx2 v[184:185], v[174:175], off nt
	global_load_dwordx2 v[182:183], v[174:175], off offset:32 nt
	global_load_dwordx2 v[180:181], v[174:175], off offset:256 nt
	global_load_dwordx2 v[178:179], v[174:175], off offset:288 nt
	global_load_dwordx2 v[172:173], v[162:163], off nt
	global_load_dwordx2 v[170:171], v[162:163], off offset:32 nt
	global_load_dwordx2 v[168:169], v[162:163], off offset:256 nt
	global_load_dwordx2 v[166:167], v[162:163], off offset:288 nt
	v_and_b32_e32 v204, 64, v202
	v_xor_b32_e32 v203, 16, v202
	v_add_u32_e32 v204, 64, v204
	v_xor_b32_e32 v205, 32, v202
	v_cmp_lt_i32_e32 vcc, v203, v204
	s_waitcnt vmcnt(0)
	v_lshlrev_b32_e32 v216, 16, v208
	v_cndmask_b32_e32 v203, v202, v203, vcc
	v_cmp_lt_i32_e32 vcc, v205, v204
	v_and_b32_e32 v217, 0xffff0000, v208
	v_lshlrev_b32_e32 v218, 16, v210
	v_and_b32_e32 v219, 0xffff0000, v210
	v_cndmask_b32_e32 v205, v202, v205, vcc
	v_lshlrev_b32_e32 v208, 16, v209
	v_and_b32_e32 v209, 0xffff0000, v209
	v_lshlrev_b32_e32 v220, 16, v212
	v_and_b32_e32 v221, 0xffff0000, v212
	v_lshlrev_b32_e32 v222, 16, v214
	v_and_b32_e32 v223, 0xffff0000, v214
	v_pk_add_f32 v[140:141], v[140:141], v[216:217]
	v_pk_add_f32 v[136:137], v[136:137], v[218:219]
	v_lshlrev_b32_e32 v204, 2, v203
	v_lshlrev_b32_e32 v203, 2, v205
	v_lshlrev_b32_e32 v210, 16, v211
	v_and_b32_e32 v211, 0xffff0000, v211
	v_pk_add_f32 v[142:143], v[142:143], v[208:209]
	v_pk_add_f32 v[132:133], v[132:133], v[220:221]
	v_pk_add_f32 v[208:209], v[128:129], v[222:223]
	v_mul_f32_e32 v205, v141, v141
	v_cvt_pk_bf16_f32 v128, v140, v141
	v_mul_f32_e32 v141, v137, v137
	v_lshlrev_b32_e32 v212, 16, v213
	v_and_b32_e32 v213, 0xffff0000, v213
	v_pk_add_f32 v[138:139], v[138:139], v[210:211]
	v_cvt_pk_bf16_f32 v210, v136, v137
	v_mul_f32_e32 v137, v133, v133
	v_fmac_f32_e32 v205, v140, v140
	v_fmac_f32_e32 v141, v136, v136
	v_lshlrev_b32_e32 v214, 16, v215
	v_and_b32_e32 v215, 0xffff0000, v215
	v_pk_add_f32 v[134:135], v[134:135], v[212:213]
	v_mul_f32_e32 v211, v209, v209
	v_fmac_f32_e32 v137, v132, v132
	v_fmac_f32_e32 v205, v142, v142
	v_fmac_f32_e32 v141, v138, v138
	v_pk_add_f32 v[130:131], v[130:131], v[214:215]
	v_cvt_pk_bf16_f32 v129, v142, v143
	v_fmac_f32_e32 v211, v208, v208
	v_fmac_f32_e32 v137, v134, v134
	v_fmac_f32_e32 v205, v143, v143
	v_fmac_f32_e32 v141, v139, v139
	global_store_dwordx2 v[206:207], v[128:129], off
	v_fmac_f32_e32 v137, v135, v135
	v_add_f32_e32 v128, v205, v141
	v_fmac_f32_e32 v211, v130, v130
	v_add_f32_e32 v128, v128, v137
	v_fmac_f32_e32 v211, v131, v131
	v_add_f32_e32 v128, v128, v211
	ds_bpermute_b32 v129, v204, v128
	v_cvt_pk_bf16_f32 v132, v132, v133
	v_cvt_pk_bf16_f32 v133, v134, v135
	v_cvt_pk_bf16_f32 v211, v138, v139
	global_store_dwordx2 v[206:207], v[132:133], off offset:256
	s_waitcnt lgkmcnt(0)
	v_add_f32_e32 v128, v128, v129
	ds_bpermute_b32 v129, v203, v128
	v_cvt_pk_bf16_f32 v132, v208, v209
	v_cvt_pk_bf16_f32 v133, v130, v131
	global_store_dwordx2 v[206:207], v[210:211], off offset:32
	global_store_dwordx2 v[206:207], v[132:133], off offset:288
	s_and_saveexec_b64 s[18:19], s[4:5]
	s_cbranch_execz .LBB0_632
	s_waitcnt lgkmcnt(0)
	v_add_f32_e32 v128, v128, v129
	v_fma_f32 v128, v128, s58, 0.5
	v_trunc_f32_e32 v128, v128
	v_mul_f32_e32 v129, 0x2f800000, v128
	v_floor_f32_e32 v129, v129
	v_fmac_f32_e32 v128, 0xcf800000, v129
	v_cvt_u32_f32_e32 v128, v128
	v_cvt_u32_f32_e32 v129, v129
	v_lshl_add_u64 v[130:131], v[156:157], 3, s[12:13]
	global_atomic_add_x2 v[130:131], v[128:129], off

; __device__ __forceinline__ uint2 pack4(f32x4 v) { return make_uint2(pack2(v[0], v[1]), pack2(v[2], v[3])); }
;   __device__ __forceinline__ void operator()(const AccT& acc, const Unit& u, int wr, int wc, int fr, int fq) const {
;     ...
;     for (int ai = 0; ai < 2; ++ai) {
;       f32x4 rv[4][2][2];
; #pragma unroll
;       for (int m = 0; m < 4; ++m) {
;         const size_t ro = (size_t)EPI_ROW(u, ai, m) * DM;
; #pragma unroll
;         for (int bj = 0; bj < 2; ++bj)
; #pragma unroll
;           for (int n = 0; n < 2; ++n) {
;             if (RF32) rv[m][bj][n] = *(const f32x4*)(resid32 + ro + EPI_COL(u, bj, n));
;             else {
;               const uint2 pk = *(const uint2*)(xb + ro + EPI_COL(u, bj, n));
;               rv[m][bj][n] = (f32x4){__uint_as_float(pk.x << 16), __uint_as_float(pk.x & 0xffff0000u), __uint_as_float(pk.y << 16), __uint_as_float(pk.y & 0xffff0000u)};
;             }
;           }
;       }
; #pragma unroll
;       for (int m = 0; m < 4; ++m) {
;         const int row = EPI_ROW(u, ai, m);
;         const size_t ro = (size_t)row * DM;
;         float ss = 0.f;
; #pragma unroll
;         for (int bj = 0; bj < 2; ++bj)
; #pragma unroll
;           for (int n = 0; n < 2; ++n) {
;             const f32x4 x = rv[m][bj][n] + acc[ai][bj][m][n];
;             ss += x[0] * x[0] + x[1] * x[1] + x[2] * x[2] + x[3] * x[3];
;             *(uint2*)(xb + ro + EPI_COL(u, bj, n)) = pack4(x);
;           }
;         ss += __shfl_xor(ss, 16);
;         ss += __shfl_xor(ss, 32);
;         if (fq == 0) atomicAdd(rowss + row, (unsigned long long)(ss * SS_FIX + 0.5f));
.LBB0_638:
	s_or_b64 exec, exec, s[18:19]
	v_add_u32_e32 v108, 0x80, v156
	v_ashrrev_i32_e32 v109, 31, v108
	s_waitcnt lgkmcnt(0)
	v_lshlrev_b64 v[80:81], 11, v[108:109]
	v_lshl_add_u64 v[80:81], s[54:55], 0, v[80:81]
	v_lshl_add_u64 v[118:119], v[80:81], 0, v[158:159]
	global_load_dwordx2 v[120:121], v[118:119], off nt
	global_load_dwordx2 v[122:123], v[118:119], off offset:32 nt
	global_load_dwordx2 v[124:125], v[118:119], off offset:256 nt
	global_load_dwordx2 v[126:127], v[118:119], off offset:288 nt
	v_add_u32_e32 v96, 0x90, v156
	v_add_u32_e32 v84, 0xa0, v156
	v_add_u32_e32 v80, 0xb0, v156
	v_ashrrev_i32_e32 v97, 31, v96
	v_ashrrev_i32_e32 v85, 31, v84
	v_ashrrev_i32_e32 v81, 31, v80
	v_lshlrev_b64 v[82:83], 11, v[96:97]
	v_lshlrev_b64 v[86:87], 11, v[84:85]
	v_lshlrev_b64 v[88:89], 11, v[80:81]
	v_lshl_add_u64 v[82:83], s[54:55], 0, v[82:83]
	v_lshl_add_u64 v[86:87], s[54:55], 0, v[86:87]
	v_lshl_add_u64 v[88:89], s[54:55], 0, v[88:89]
	v_lshl_add_u64 v[106:107], v[82:83], 0, v[158:159]
	v_lshl_add_u64 v[94:95], v[86:87], 0, v[158:159]
	v_lshl_add_u64 v[82:83], v[88:89], 0, v[158:159]
	global_load_dwordx2 v[116:117], v[106:107], off nt
	global_load_dwordx2 v[114:115], v[106:107], off offset:32 nt
	global_load_dwordx2 v[112:113], v[106:107], off offset:256 nt
	global_load_dwordx2 v[110:111], v[106:107], off offset:288 nt
	global_load_dwordx2 v[104:105], v[94:95], off nt
	global_load_dwordx2 v[102:103], v[94:95], off offset:32 nt
	global_load_dwordx2 v[100:101], v[94:95], off offset:256 nt
	global_load_dwordx2 v[98:99], v[94:95], off offset:288 nt
	global_load_dwordx2 v[92:93], v[82:83], off nt
	global_load_dwordx2 v[90:91], v[82:83], off offset:32 nt
	global_load_dwordx2 v[88:89], v[82:83], off offset:256 nt
	global_load_dwordx2 v[86:87], v[82:83], off offset:288 nt
	s_waitcnt vmcnt(15)
	v_lshlrev_b32_e32 v128, 16, v120
	v_and_b32_e32 v129, 0xffff0000, v120
	s_waitcnt vmcnt(14)
	v_lshlrev_b32_e32 v130, 16, v122
	v_and_b32_e32 v131, 0xffff0000, v122
	v_lshlrev_b32_e32 v120, 16, v121
	v_and_b32_e32 v121, 0xffff0000, v121
	v_lshlrev_b32_e32 v122, 16, v123
	v_and_b32_e32 v123, 0xffff0000, v123
	s_waitcnt vmcnt(13)
	v_lshlrev_b32_e32 v132, 16, v124
	v_and_b32_e32 v133, 0xffff0000, v124
	s_waitcnt vmcnt(12)
	v_lshlrev_b32_e32 v134, 16, v126
	v_and_b32_e32 v135, 0xffff0000, v126
	v_pk_add_f32 v[76:77], v[76:77], v[128:129]
	v_pk_add_f32 v[72:73], v[72:73], v[130:131]
	v_pk_add_f32 v[78:79], v[78:79], v[120:121]
	v_pk_add_f32 v[74:75], v[74:75], v[122:123]
	v_pk_add_f32 v[68:69], v[68:69], v[132:133]
	v_pk_add_f32 v[120:121], v[64:65], v[134:135]
	v_mul_f32_e32 v123, v77, v77
	v_cvt_pk_bf16_f32 v64, v76, v77
	v_mul_f32_e32 v77, v73, v73
	v_lshlrev_b32_e32 v124, 16, v125
	v_and_b32_e32 v125, 0xffff0000, v125
	v_cvt_pk_bf16_f32 v122, v72, v73
	v_mul_f32_e32 v73, v69, v69
	v_fmac_f32_e32 v123, v76, v76
	v_fmac_f32_e32 v77, v72, v72
	v_lshlrev_b32_e32 v126, 16, v127
	v_and_b32_e32 v127, 0xffff0000, v127
	v_pk_add_f32 v[70:71], v[70:71], v[124:125]
	v_mul_f32_e32 v124, v121, v121
	v_fmac_f32_e32 v73, v68, v68
	v_fmac_f32_e32 v123, v78, v78
	v_fmac_f32_e32 v77, v74, v74
	v_pk_add_f32 v[66:67], v[66:67], v[126:127]
	v_cvt_pk_bf16_f32 v65, v78, v79
	v_fmac_f32_e32 v124, v120, v120
	v_fmac_f32_e32 v73, v70, v70
	v_fmac_f32_e32 v123, v79, v79
	v_fmac_f32_e32 v77, v75, v75
	global_store_dwordx2 v[118:119], v[64:65], off
	v_fmac_f32_e32 v124, v66, v66
	v_fmac_f32_e32 v73, v71, v71
	v_add_f32_e32 v64, v123, v77
	v_add_f32_e32 v64, v64, v73
	v_fmac_f32_e32 v124, v67, v67
	v_add_f32_e32 v64, v64, v124
	ds_bpermute_b32 v65, v204, v64
	v_cvt_pk_bf16_f32 v68, v68, v69
	v_cvt_pk_bf16_f32 v69, v70, v71
	v_cvt_pk_bf16_f32 v123, v74, v75
	global_store_dwordx2 v[118:119], v[68:69], off offset:256
	s_waitcnt lgkmcnt(0)
	v_add_f32_e32 v64, v64, v65
	ds_bpermute_b32 v65, v203, v64
	v_cvt_pk_bf16_f32 v68, v120, v121
	v_cvt_pk_bf16_f32 v69, v66, v67
	global_store_dwordx2 v[118:119], v[122:123], off offset:32
	global_store_dwordx2 v[118:119], v[68:69], off offset:288
	s_and_saveexec_b64 s[18:19], s[4:5]
	s_cbranch_execz .LBB0_640
	s_waitcnt lgkmcnt(0)
	v_add_f32_e32 v64, v64, v65
	v_fma_f32 v64, v64, s58, 0.5
	v_trunc_f32_e32 v64, v64
	v_mul_f32_e32 v65, 0x2f800000, v64
	v_floor_f32_e32 v65, v65
	v_fmac_f32_e32 v64, 0xcf800000, v65
	v_cvt_u32_f32_e32 v64, v64
	v_cvt_u32_f32_e32 v65, v65
	v_lshl_add_u64 v[66:67], v[108:109], 3, s[12:13]
	global_atomic_add_x2 v[66:67], v[64:65], off

; #define PG8_STAGE(bufoff, gbase, voff) do { _Pragma("unroll") for (int _i = 0; _i < 2; ++_i) \
;     __builtin_amdgcn_global_load_lds((const unsigned*)((const char*)(gbase) + (voff)[_i]), (LAS unsigned*)(lds + (bufoff) + ldsw + _i * 8192), 16, 0, 0); } while (0)
; #define PG8_LDB(dst, b, h) do { \
;     PG8_DSR(dst[0][0], baddr, ((b) * 2 + (h)) * PG_HTB + 0 * 2048 + 0);    PG8_DSR(dst[0][1], baddr, ((b) * 2 + (h)) * PG_HTB + 0 * 2048 + 1024); \
;     PG8_DSR(dst[1][0], baddr, ((b) * 2 + (h)) * PG_HTB + 1 * 2048 + 0);    PG8_DSR(dst[1][1], baddr, ((b) * 2 + (h)) * PG_HTB + 1 * 2048 + 1024); } while (0)
; #define PG8_MMA(ai, bj, At, Bt) do { __builtin_amdgcn_s_setprio(1); _Pragma("unroll") for (int m = 0; m < 4; ++m) _Pragma("unroll") for (int n = 0; n < 2; ++n) _Pragma("unroll") for (int k = 0; k < 2; ++k) \
;     acc[ai][bj][m][n] = __builtin_amdgcn_mfma_f32_16x16x32_bf16(Bt[n][k], At[m][k], acc[ai][bj][m][n], 0, 0, 0); __builtin_amdgcn_s_setprio(0); } while (0)
; #define PG8_WAIT_V(n) asm volatile("s_waitcnt vmcnt(" #n ")" ::: "memory")
; #define PG8_WAIT_L(n) asm volatile("s_waitcnt lgkmcnt(" #n ")" ::: "memory")
; #define PG8_WAIT_L0 asm volatile("s_waitcnt lgkmcnt(0)" \
;     : "+v"(At[0][0]), "+v"(At[0][1]), "+v"(At[1][0]), "+v"(At[1][1]), "+v"(At[2][0]), "+v"(At[2][1]), "+v"(At[3][0]), "+v"(At[3][1]), \
;       "+v"(B0[0][0]), "+v"(B0[0][1]), "+v"(B0[1][0]), "+v"(B0[1][1]), "+v"(B1[0][0]), "+v"(B1[0][1]), "+v"(B1[1][0]), "+v"(B1[1][1]) :: "memory")
; #define PG8_BAR __builtin_amdgcn_s_barrier()
; #define PG8_SCHED __builtin_amdgcn_sched_barrier(0)
; template <class Epi>
; __device__ __forceinline__ void gemm_phase(LAS unsigned char* lds, const Gemm g, const StaticOrder& S, const Epi& E) {
;     ...
;       PG8_LDB(B0, 0, 0); PG8_SCHED; PG8_LDA(At, 0, 0); PG8_STAGE(PG8_SA(1, 1), a1 + hstep, voffA);
;       PG8_WAIT_L(8); PG8_BAR; PG8_WAIT_L0; PG8_MMA(0, 0, At, B0); PG8_BAR; PG8_SCHED;
;       PG8_LDB(B1, 0, 1); PG8_STAGE(PG8_SB(0, 0), b2, voffA);
;       PG8_BAR; PG8_WAIT_L0; PG8_MMA(0, 1, At, B1); PG8_BAR;
;       PG8_LDA(At, 0, 1); PG8_STAGE(PG8_SA(0, 0), a2, voffA);
;       PG8_BAR; PG8_WAIT_L0; PG8_MMA(1, 0, At, B0); PG8_BAR; PG8_SCHED;
;       PG8_STAGE(PG8_SB(0, 1), b2 + hstep, voffA);
;       PG8_WAIT_V(6); PG8_BAR; PG8_MMA(1, 1, At, B1); PG8_BAR;
.LBB0_1422:
	ds_read_b128 v[156:159], v200 offset:0
	ds_read_b128 v[160:163], v200 offset:0x400
	ds_read_b128 v[164:167], v200 offset:0x800
	s_add_u32 s26, s24, 0xfffc0080
	ds_read_b128 v[168:171], v200 offset:0xc00
	s_addc_u32 s27, s25, -1
	s_cmp_eq_u32 s59, 12
	s_cselect_b32 s29, s15, s27
	s_cselect_b32 s28, s21, s26
	ds_read_b128 v[172:175], v199 offset:0
	ds_read_b128 v[176:179], v199 offset:0x400
	ds_read_b128 v[180:183], v199 offset:0x800
	ds_read_b128 v[184:187], v199 offset:0xc00
	ds_read_b128 v[188:191], v199 offset:0x1000
	ds_read_b128 v[194:197], v199 offset:0x1400
	ds_read_b128 v[204:207], v199 offset:0x1800
	s_mov_b32 m0, s47
	ds_read_b128 v[208:211], v199 offset:0x1c00
	v_lshl_add_u64 v[212:213], s[24:25], 0, v[148:149]
	global_load_lds_dwordx4 v[212:213], off
	v_lshl_add_u64 v[212:213], s[24:25], 0, v[150:151]
	s_mov_b32 m0, s48
	s_cselect_b32 s27, s13, s58
	global_load_lds_dwordx4 v[212:213], off
	s_waitcnt lgkmcnt(8)
	s_barrier
	s_waitcnt lgkmcnt(0)
	s_cselect_b32 s26, s50, s51
	s_setprio 1
	v_mfma_f32_16x16x32_bf16 v[0:3], v[156:159], v[172:175], v[140:143]
	v_mfma_f32_16x16x32_bf16 v[4:7], v[164:167], v[172:175], v[136:139]
	v_mfma_f32_16x16x32_bf16 v[8:11], v[156:159], v[180:183], v[124:127]
	v_mfma_f32_16x16x32_bf16 v[12:15], v[164:167], v[180:183], v[120:123]
	v_mfma_f32_16x16x32_bf16 v[108:111], v[156:159], v[188:191], v[108:111]
	v_mfma_f32_16x16x32_bf16 v[104:107], v[164:167], v[188:191], v[104:107]
	v_mfma_f32_16x16x32_bf16 v[92:95], v[156:159], v[204:207], v[92:95]
	v_mfma_f32_16x16x32_bf16 v[88:91], v[164:167], v[204:207], v[88:91]
	v_mfma_f32_16x16x32_bf16 v[0:3], v[160:163], v[176:179], v[0:3]
	v_mfma_f32_16x16x32_bf16 v[4:7], v[168:171], v[176:179], v[4:7]
	v_mfma_f32_16x16x32_bf16 v[8:11], v[160:163], v[184:187], v[8:11]
	v_mfma_f32_16x16x32_bf16 v[12:15], v[168:171], v[184:187], v[12:15]
	v_mfma_f32_16x16x32_bf16 v[108:111], v[160:163], v[194:197], v[108:111]
	v_mfma_f32_16x16x32_bf16 v[104:107], v[168:171], v[194:197], v[104:107]
	v_mfma_f32_16x16x32_bf16 v[92:95], v[160:163], v[208:211], v[92:95]
	v_mfma_f32_16x16x32_bf16 v[88:91], v[168:171], v[208:211], v[88:91]
	s_setprio 0
	s_barrier
	ds_read_b128 v[120:123], v200 offset:0x4000
	ds_read_b128 v[124:127], v200 offset:0x4400
	ds_read_b128 v[136:139], v200 offset:0x4800
	s_mov_b32 m0, s23
	ds_read_b128 v[140:143], v200 offset:0x4c00
	v_lshl_add_u64 v[212:213], s[26:27], 0, v[144:145]
	global_load_lds_dwordx4 v[212:213], off
	v_lshl_add_u64 v[214:215], s[26:27], 0, v[146:147]
	s_mov_b32 m0, s30
	s_nop 0
	global_load_lds_dwordx4 v[214:215], off
	s_barrier
	s_waitcnt lgkmcnt(0)
	s_setprio 1
	v_mfma_f32_16x16x32_bf16 v[132:135], v[120:123], v[172:175], v[132:135]
	v_mfma_f32_16x16x32_bf16 v[128:131], v[136:139], v[172:175], v[128:131]
	v_mfma_f32_16x16x32_bf16 v[116:119], v[120:123], v[180:183], v[116:119]
	v_mfma_f32_16x16x32_bf16 v[112:115], v[136:139], v[180:183], v[112:115]
	v_mfma_f32_16x16x32_bf16 v[100:103], v[120:123], v[188:191], v[100:103]
	v_mfma_f32_16x16x32_bf16 v[96:99], v[136:139], v[188:191], v[96:99]
	v_mfma_f32_16x16x32_bf16 v[84:87], v[120:123], v[204:207], v[84:87]
	v_mfma_f32_16x16x32_bf16 v[80:83], v[136:139], v[204:207], v[80:83]
	v_mfma_f32_16x16x32_bf16 v[132:135], v[124:127], v[176:179], v[132:135]
	v_mfma_f32_16x16x32_bf16 v[128:131], v[140:143], v[176:179], v[128:131]
	v_mfma_f32_16x16x32_bf16 v[116:119], v[124:127], v[184:187], v[116:119]
	v_mfma_f32_16x16x32_bf16 v[112:115], v[140:143], v[184:187], v[112:115]
	v_mfma_f32_16x16x32_bf16 v[100:103], v[124:127], v[194:197], v[100:103]
	v_mfma_f32_16x16x32_bf16 v[96:99], v[140:143], v[194:197], v[96:99]
	v_mfma_f32_16x16x32_bf16 v[84:87], v[124:127], v[208:211], v[84:87]
	v_mfma_f32_16x16x32_bf16 v[80:83], v[140:143], v[208:211], v[80:83]
	s_setprio 0
	s_barrier
	ds_read_b128 v[172:175], v199 offset:0x4000
	ds_read_b128 v[176:179], v199 offset:0x4400
	ds_read_b128 v[180:183], v199 offset:0x4800
	ds_read_b128 v[184:187], v199 offset:0x4c00
	ds_read_b128 v[188:191], v199 offset:0x5000
	ds_read_b128 v[194:197], v199 offset:0x5400
	ds_read_b128 v[204:207], v199 offset:0x5800
	s_mov_b32 m0, s3
	ds_read_b128 v[208:211], v199 offset:0x5c00
	v_lshl_add_u64 v[216:217], s[28:29], 0, v[144:145]
	global_load_lds_dwordx4 v[216:217], off
	v_lshl_add_u64 v[218:219], s[28:29], 0, v[146:147]
	s_mov_b32 m0, s31
	s_nop 0
	global_load_lds_dwordx4 v[218:219], off
	s_barrier
	s_waitcnt lgkmcnt(0)
	s_setprio 1
	v_mfma_f32_16x16x32_bf16 v[76:79], v[156:159], v[172:175], v[76:79]
	v_mfma_f32_16x16x32_bf16 v[72:75], v[164:167], v[172:175], v[72:75]
	v_mfma_f32_16x16x32_bf16 v[60:63], v[156:159], v[180:183], v[60:63]
	v_mfma_f32_16x16x32_bf16 v[56:59], v[164:167], v[180:183], v[56:59]
	v_mfma_f32_16x16x32_bf16 v[44:47], v[156:159], v[188:191], v[44:47]
	v_mfma_f32_16x16x32_bf16 v[40:43], v[164:167], v[188:191], v[40:43]
	v_mfma_f32_16x16x32_bf16 v[28:31], v[156:159], v[204:207], v[28:31]
	v_mfma_f32_16x16x32_bf16 v[24:27], v[164:167], v[204:207], v[24:27]
	v_mfma_f32_16x16x32_bf16 v[76:79], v[160:163], v[176:179], v[76:79]
	v_mfma_f32_16x16x32_bf16 v[72:75], v[168:171], v[176:179], v[72:75]
	v_mfma_f32_16x16x32_bf16 v[60:63], v[160:163], v[184:187], v[60:63]
	v_mfma_f32_16x16x32_bf16 v[56:59], v[168:171], v[184:187], v[56:59]
	v_mfma_f32_16x16x32_bf16 v[44:47], v[160:163], v[194:197], v[44:47]
	v_mfma_f32_16x16x32_bf16 v[40:43], v[168:171], v[194:197], v[40:43]
	v_mfma_f32_16x16x32_bf16 v[28:31], v[160:163], v[208:211], v[28:31]
	v_mfma_f32_16x16x32_bf16 v[24:27], v[168:171], v[208:211], v[24:27]
	s_setprio 0
	s_barrier
; #define PG8_STAGE(bufoff, gbase, voff) do { _Pragma("unroll") for (int _i = 0; _i < 2; ++_i) \
;     __builtin_amdgcn_global_load_lds((const unsigned*)((const char*)(gbase) + (voff)[_i]), (LAS unsigned*)(lds + (bufoff) + ldsw + _i * 8192), 16, 0, 0); } while (0)
; #define PG8_LDB(dst, b, h) do { \
;     PG8_DSR(dst[0][0], baddr, ((b) * 2 + (h)) * PG_HTB + 0 * 2048 + 0);    PG8_DSR(dst[0][1], baddr, ((b) * 2 + (h)) * PG_HTB + 0 * 2048 + 1024); \
;     PG8_DSR(dst[1][0], baddr, ((b) * 2 + (h)) * PG_HTB + 1 * 2048 + 0);    PG8_DSR(dst[1][1], baddr, ((b) * 2 + (h)) * PG_HTB + 1 * 2048 + 1024); } while (0)
; #define PG8_MMA(ai, bj, At, Bt) do { __builtin_amdgcn_s_setprio(1); _Pragma("unroll") for (int m = 0; m < 4; ++m) _Pragma("unroll") for (int n = 0; n < 2; ++n) _Pragma("unroll") for (int k = 0; k < 2; ++k) \
;     acc[ai][bj][m][n] = __builtin_amdgcn_mfma_f32_16x16x32_bf16(Bt[n][k], At[m][k], acc[ai][bj][m][n], 0, 0, 0); __builtin_amdgcn_s_setprio(0); } while (0)
; #define PG8_WAIT_V(n) asm volatile("s_waitcnt vmcnt(" #n ")" ::: "memory")
; #define PG8_WAIT_L(n) asm volatile("s_waitcnt lgkmcnt(" #n ")" ::: "memory")
; #define PG8_WAIT_L0 asm volatile("s_waitcnt lgkmcnt(0)" \
;     : "+v"(At[0][0]), "+v"(At[0][1]), "+v"(At[1][0]), "+v"(At[1][1]), "+v"(At[2][0]), "+v"(At[2][1]), "+v"(At[3][0]), "+v"(At[3][1]), \
;       "+v"(B0[0][0]), "+v"(B0[0][1]), "+v"(B0[1][0]), "+v"(B0[1][1]), "+v"(B1[0][0]), "+v"(B1[0][1]), "+v"(B1[1][0]), "+v"(B1[1][1]) :: "memory")
; #define PG8_BAR __builtin_amdgcn_s_barrier()
; #define PG8_SCHED __builtin_amdgcn_sched_barrier(0)
; template <class Epi>
; __device__ __forceinline__ void gemm_phase(LAS unsigned char* lds, const Gemm g, const StaticOrder& S, const Epi& E) {
;     ...
;       PG8_WAIT_V(6); PG8_BAR; PG8_MMA(1, 1, At, B1); PG8_BAR;
;       PG8_LDB(B0, 1, 0); PG8_SCHED; PG8_LDA(At, 1, 0); PG8_STAGE(PG8_SA(0, 1), a2 + hstep, voffA);
;       PG8_WAIT_L(8); PG8_BAR; PG8_WAIT_L0; PG8_MMA(0, 0, At, B0); PG8_BAR; PG8_SCHED;
;       PG8_LDB(B1, 1, 1); PG8_STAGE(PG8_SB(1, 0), b3, voffA);
;       PG8_BAR; PG8_WAIT_L0; PG8_MMA(0, 1, At, B1); PG8_BAR;
;       PG8_LDA(At, 1, 1); PG8_STAGE(PG8_SA(1, 0), a3, voffA);
;       PG8_BAR; PG8_WAIT_L0; PG8_MMA(1, 0, At, B0); PG8_BAR; PG8_SCHED;
;       PG8_STAGE(PG8_SB(1, 1), b3 + hstep, voffA);
	s_add_u32 s60, s26, 0x40000
	s_addc_u32 s61, s27, 0
	s_mov_b32 m0, s34
	v_lshl_add_u64 v[156:157], s[60:61], 0, v[144:145]
	global_load_lds_dwordx4 v[156:157], off
	v_lshl_add_u64 v[156:157], s[60:61], 0, v[146:147]
	s_mov_b32 m0, s35
	s_nop 0
	global_load_lds_dwordx4 v[156:157], off
	s_waitcnt vmcnt(6)
	s_barrier
	s_setprio 1
	v_mfma_f32_16x16x32_bf16 v[68:71], v[120:123], v[172:175], v[68:71]
	v_mfma_f32_16x16x32_bf16 v[64:67], v[136:139], v[172:175], v[64:67]
	v_mfma_f32_16x16x32_bf16 v[52:55], v[120:123], v[180:183], v[52:55]
	v_mfma_f32_16x16x32_bf16 v[48:51], v[136:139], v[180:183], v[48:51]
	v_mfma_f32_16x16x32_bf16 v[36:39], v[120:123], v[188:191], v[36:39]
	v_mfma_f32_16x16x32_bf16 v[32:35], v[136:139], v[188:191], v[32:35]
	v_mfma_f32_16x16x32_bf16 v[20:23], v[120:123], v[204:207], v[20:23]
	v_mfma_f32_16x16x32_bf16 v[16:19], v[136:139], v[204:207], v[16:19]
	v_mfma_f32_16x16x32_bf16 v[68:71], v[124:127], v[176:179], v[68:71]
	v_mfma_f32_16x16x32_bf16 v[64:67], v[140:143], v[176:179], v[64:67]
	v_mfma_f32_16x16x32_bf16 v[52:55], v[124:127], v[184:187], v[52:55]
	v_mfma_f32_16x16x32_bf16 v[48:51], v[140:143], v[184:187], v[48:51]
	v_mfma_f32_16x16x32_bf16 v[36:39], v[124:127], v[194:197], v[36:39]
	v_mfma_f32_16x16x32_bf16 v[32:35], v[140:143], v[194:197], v[32:35]
	v_mfma_f32_16x16x32_bf16 v[20:23], v[124:127], v[208:211], v[20:23]
	v_mfma_f32_16x16x32_bf16 v[16:19], v[140:143], v[208:211], v[16:19]
	s_setprio 0
	s_barrier
	ds_read_b128 v[156:159], v200 offset:0x8000
	ds_read_b128 v[160:163], v200 offset:0x8400
	ds_read_b128 v[164:167], v200 offset:0x8800
	ds_read_b128 v[168:171], v200 offset:0x8c00
	ds_read_b128 v[172:175], v199 offset:0x8000
	ds_read_b128 v[176:179], v199 offset:0x8400
	ds_read_b128 v[180:183], v199 offset:0x8800
	ds_read_b128 v[184:187], v199 offset:0x8c00
	ds_read_b128 v[188:191], v199 offset:0x9000
	ds_read_b128 v[194:197], v199 offset:0x9400
	s_add_u32 s28, s28, 0x40000
	ds_read_b128 v[204:207], v199 offset:0x9800
	s_addc_u32 s29, s29, 0
	s_mov_b32 m0, s36
	ds_read_b128 v[208:211], v199 offset:0x9c00
	v_lshl_add_u64 v[220:221], s[28:29], 0, v[144:145]
	global_load_lds_dwordx4 v[220:221], off
	v_lshl_add_u64 v[220:221], s[28:29], 0, v[146:147]
	s_mov_b32 m0, s37
	s_nop 0
	global_load_lds_dwordx4 v[220:221], off
	s_waitcnt lgkmcnt(8)
	s_barrier
	s_waitcnt lgkmcnt(0)
	s_setprio 1
	v_mfma_f32_16x16x32_bf16 v[0:3], v[156:159], v[172:175], v[0:3]
	v_mfma_f32_16x16x32_bf16 v[140:143], v[160:163], v[176:179], v[0:3]
	v_mfma_f32_16x16x32_bf16 v[0:3], v[164:167], v[172:175], v[4:7]
	v_mfma_f32_16x16x32_bf16 v[136:139], v[168:171], v[176:179], v[0:3]
	v_mfma_f32_16x16x32_bf16 v[0:3], v[156:159], v[180:183], v[8:11]
	v_mfma_f32_16x16x32_bf16 v[124:127], v[160:163], v[184:187], v[0:3]
	v_mfma_f32_16x16x32_bf16 v[0:3], v[164:167], v[180:183], v[12:15]
	v_mfma_f32_16x16x32_bf16 v[120:123], v[168:171], v[184:187], v[0:3]
	v_mfma_f32_16x16x32_bf16 v[0:3], v[156:159], v[188:191], v[108:111]
	v_mfma_f32_16x16x32_bf16 v[108:111], v[160:163], v[194:197], v[0:3]
	v_mfma_f32_16x16x32_bf16 v[0:3], v[164:167], v[188:191], v[104:107]
	v_mfma_f32_16x16x32_bf16 v[104:107], v[168:171], v[194:197], v[0:3]
	v_mfma_f32_16x16x32_bf16 v[0:3], v[156:159], v[204:207], v[92:95]
	v_mfma_f32_16x16x32_bf16 v[92:95], v[160:163], v[208:211], v[0:3]
	v_mfma_f32_16x16x32_bf16 v[0:3], v[164:167], v[204:207], v[88:91]
	v_mfma_f32_16x16x32_bf16 v[88:91], v[168:171], v[208:211], v[0:3]
	s_setprio 0
	s_barrier
	ds_read_b128 v[12:15], v200 offset:0xc000
	ds_read_b128 v[8:11], v200 offset:0xc400
	ds_read_b128 v[4:7], v200 offset:0xc800
	s_mov_b32 m0, s38
	ds_read_b128 v[0:3], v200 offset:0xcc00
	v_lshl_add_u64 v[212:213], v[212:213], 0, s[10:11]
	global_load_lds_dwordx4 v[212:213], off
	v_lshl_add_u64 v[212:213], v[214:215], 0, s[10:11]
	s_mov_b32 m0, s39
	s_nop 0
	global_load_lds_dwordx4 v[212:213], off
	s_barrier
	s_waitcnt lgkmcnt(0)
	s_setprio 1
	v_mfma_f32_16x16x32_bf16 v[132:135], v[12:15], v[172:175], v[132:135]
	v_mfma_f32_16x16x32_bf16 v[128:131], v[4:7], v[172:175], v[128:131]
	v_mfma_f32_16x16x32_bf16 v[116:119], v[12:15], v[180:183], v[116:119]
	v_mfma_f32_16x16x32_bf16 v[112:115], v[4:7], v[180:183], v[112:115]
	v_mfma_f32_16x16x32_bf16 v[100:103], v[12:15], v[188:191], v[100:103]
	v_mfma_f32_16x16x32_bf16 v[96:99], v[4:7], v[188:191], v[96:99]
	v_mfma_f32_16x16x32_bf16 v[84:87], v[12:15], v[204:207], v[84:87]
	v_mfma_f32_16x16x32_bf16 v[80:83], v[4:7], v[204:207], v[80:83]
	v_mfma_f32_16x16x32_bf16 v[132:135], v[8:11], v[176:179], v[132:135]
	v_mfma_f32_16x16x32_bf16 v[128:131], v[0:3], v[176:179], v[128:131]
	v_mfma_f32_16x16x32_bf16 v[116:119], v[8:11], v[184:187], v[116:119]
	v_mfma_f32_16x16x32_bf16 v[112:115], v[0:3], v[184:187], v[112:115]
	v_mfma_f32_16x16x32_bf16 v[100:103], v[8:11], v[194:197], v[100:103]
	v_mfma_f32_16x16x32_bf16 v[96:99], v[0:3], v[194:197], v[96:99]
	v_mfma_f32_16x16x32_bf16 v[84:87], v[8:11], v[208:211], v[84:87]
	v_mfma_f32_16x16x32_bf16 v[80:83], v[0:3], v[208:211], v[80:83]
	s_setprio 0
	s_barrier
	ds_read_b128 v[172:175], v199 offset:0xc000
	ds_read_b128 v[176:179], v199 offset:0xc400
	ds_read_b128 v[180:183], v199 offset:0xc800
	ds_read_b128 v[184:187], v199 offset:0xcc00
	ds_read_b128 v[188:191], v199 offset:0xd000
	ds_read_b128 v[194:197], v199 offset:0xd400
	ds_read_b128 v[204:207], v199 offset:0xd800
	s_mov_b32 m0, s40
	ds_read_b128 v[208:211], v199 offset:0xdc00
	v_lshl_add_u64 v[212:213], v[216:217], 0, s[10:11]
	global_load_lds_dwordx4 v[212:213], off
	v_lshl_add_u64 v[212:213], v[218:219], 0, s[10:11]
	s_mov_b32 m0, s41
	s_nop 0
	global_load_lds_dwordx4 v[212:213], off
	s_barrier
; #define PG8_STAGE(bufoff, gbase, voff) do { _Pragma("unroll") for (int _i = 0; _i < 2; ++_i) \
;     __builtin_amdgcn_global_load_lds((const unsigned*)((const char*)(gbase) + (voff)[_i]), (LAS unsigned*)(lds + (bufoff) + ldsw + _i * 8192), 16, 0, 0); } while (0)
; #define PG8_MMA(ai, bj, At, Bt) do { __builtin_amdgcn_s_setprio(1); _Pragma("unroll") for (int m = 0; m < 4; ++m) _Pragma("unroll") for (int n = 0; n < 2; ++n) _Pragma("unroll") for (int k = 0; k < 2; ++k) \
;     acc[ai][bj][m][n] = __builtin_amdgcn_mfma_f32_16x16x32_bf16(Bt[n][k], At[m][k], acc[ai][bj][m][n], 0, 0, 0); __builtin_amdgcn_s_setprio(0); } while (0)
; #define PG8_WAIT_V(n) asm volatile("s_waitcnt vmcnt(" #n ")" ::: "memory")
; #define PG8_BAR __builtin_amdgcn_s_barrier()
; template <class Epi>
; __device__ __forceinline__ void gemm_phase(LAS unsigned char* lds, const Gemm g, const StaticOrder& S, const Epi& E) {
;     ...
;       PG8_STAGE(PG8_SB(1, 1), b3 + hstep, voffA);
;       PG8_WAIT_V(6); PG8_BAR; PG8_MMA(1, 1, At, B1); PG8_BAR;
	s_waitcnt lgkmcnt(0)
	s_setprio 1
	v_mfma_f32_16x16x32_bf16 v[76:79], v[156:159], v[172:175], v[76:79]
	v_mfma_f32_16x16x32_bf16 v[72:75], v[164:167], v[172:175], v[72:75]
	v_mfma_f32_16x16x32_bf16 v[60:63], v[156:159], v[180:183], v[60:63]
	v_mfma_f32_16x16x32_bf16 v[56:59], v[164:167], v[180:183], v[56:59]
	v_mfma_f32_16x16x32_bf16 v[44:47], v[156:159], v[188:191], v[44:47]
	v_mfma_f32_16x16x32_bf16 v[40:43], v[164:167], v[188:191], v[40:43]
	v_mfma_f32_16x16x32_bf16 v[28:31], v[156:159], v[204:207], v[28:31]
	v_mfma_f32_16x16x32_bf16 v[24:27], v[164:167], v[204:207], v[24:27]
	v_mfma_f32_16x16x32_bf16 v[76:79], v[160:163], v[176:179], v[76:79]
	v_mfma_f32_16x16x32_bf16 v[72:75], v[168:171], v[176:179], v[72:75]
	v_mfma_f32_16x16x32_bf16 v[60:63], v[160:163], v[184:187], v[60:63]
	v_mfma_f32_16x16x32_bf16 v[56:59], v[168:171], v[184:187], v[56:59]
	v_mfma_f32_16x16x32_bf16 v[44:47], v[160:163], v[194:197], v[44:47]
	v_mfma_f32_16x16x32_bf16 v[40:43], v[168:171], v[194:197], v[40:43]
	v_mfma_f32_16x16x32_bf16 v[28:31], v[160:163], v[208:211], v[28:31]
	v_mfma_f32_16x16x32_bf16 v[24:27], v[168:171], v[208:211], v[24:27]
	s_setprio 0
	s_barrier
	s_add_u32 s26, s26, 0x40080
	s_addc_u32 s27, s27, 0
	s_mov_b32 m0, s42
	v_lshl_add_u64 v[156:157], s[26:27], 0, v[144:145]
	global_load_lds_dwordx4 v[156:157], off
	v_lshl_add_u64 v[156:157], s[26:27], 0, v[146:147]
	s_mov_b32 m0, s43
	s_nop 0
	global_load_lds_dwordx4 v[156:157], off
	s_waitcnt vmcnt(6)
	s_barrier
	s_setprio 1
	v_mfma_f32_16x16x32_bf16 v[68:71], v[12:15], v[172:175], v[68:71]
	v_mfma_f32_16x16x32_bf16 v[64:67], v[4:7], v[172:175], v[64:67]
	v_mfma_f32_16x16x32_bf16 v[52:55], v[12:15], v[180:183], v[52:55]
	v_mfma_f32_16x16x32_bf16 v[48:51], v[4:7], v[180:183], v[48:51]
	v_mfma_f32_16x16x32_bf16 v[36:39], v[12:15], v[188:191], v[36:39]
	v_mfma_f32_16x16x32_bf16 v[32:35], v[4:7], v[188:191], v[32:35]
	v_mfma_f32_16x16x32_bf16 v[20:23], v[12:15], v[204:207], v[20:23]
	v_mfma_f32_16x16x32_bf16 v[16:19], v[4:7], v[204:207], v[16:19]
	v_mfma_f32_16x16x32_bf16 v[68:71], v[8:11], v[176:179], v[68:71]
	v_mfma_f32_16x16x32_bf16 v[64:67], v[0:3], v[176:179], v[64:67]
	v_mfma_f32_16x16x32_bf16 v[52:55], v[8:11], v[184:187], v[52:55]
	v_mfma_f32_16x16x32_bf16 v[48:51], v[0:3], v[184:187], v[48:51]
	v_mfma_f32_16x16x32_bf16 v[36:39], v[8:11], v[194:197], v[36:39]
	v_mfma_f32_16x16x32_bf16 v[32:35], v[0:3], v[194:197], v[32:35]
	v_mfma_f32_16x16x32_bf16 v[20:23], v[8:11], v[208:211], v[20:23]
	v_mfma_f32_16x16x32_bf16 v[16:19], v[0:3], v[208:211], v[16:19]
	s_setprio 0
	s_add_i32 s59, s59, 2
	s_add_u32 s24, s24, 0x100
	s_addc_u32 s25, s25, 0
	s_add_u32 s51, s51, 0x100
	s_addc_u32 s58, s58, 0
	s_cmp_gt_u32 s59, 13
	s_barrier
	s_cbranch_scc0 .LBB0_1422
; __device__ __forceinline__ uint2 pack4(f32x4 v) { return make_uint2(pack2(v[0], v[1]), pack2(v[2], v[3])); }
;   __device__ __forceinline__ void operator()(const AccT& acc, const Unit& u, int wr, int wc, int fr, int fq) const {
;     ...
;     for (int ai = 0; ai < 2; ++ai) {
;       f32x4 rv[4][2][2];
; #pragma unroll
;       for (int m = 0; m < 4; ++m) {
;         const size_t ro = (size_t)EPI_ROW(u, ai, m) * DM;
; #pragma unroll
;         for (int bj = 0; bj < 2; ++bj)
; #pragma unroll
;           for (int n = 0; n < 2; ++n) {
;             if (RF32) rv[m][bj][n] = *(const f32x4*)(resid32 + ro + EPI_COL(u, bj, n));
;             else {
;               const uint2 pk = *(const uint2*)(xb + ro + EPI_COL(u, bj, n));
;               rv[m][bj][n] = (f32x4){__uint_as_float(pk.x << 16), __uint_as_float(pk.x & 0xffff0000u), __uint_as_float(pk.y << 16), __uint_as_float(pk.y & 0xffff0000u)};
;             }
;           }
;       }
; #pragma unroll
;       for (int m = 0; m < 4; ++m) {
;         const int row = EPI_ROW(u, ai, m);
;         const size_t ro = (size_t)row * DM;
;         float ss = 0.f;
; #pragma unroll
;         for (int bj = 0; bj < 2; ++bj)
; #pragma unroll
;           for (int n = 0; n < 2; ++n) {
;             const f32x4 x = rv[m][bj][n] + acc[ai][bj][m][n];
;             ss += x[0] * x[0] + x[1] * x[1] + x[2] * x[2] + x[3] * x[3];
;             *(uint2*)(xb + ro + EPI_COL(u, bj, n)) = pack4(x);
;           }
;         ss += __shfl_xor(ss, 16);
;         ss += __shfl_xor(ss, 32);
;         if (fq == 0) atomicAdd(rowss + row, (unsigned long long)(ss * SS_FIX + 0.5f));
	v_lshl_add_u32 v156, s20, 8, v198
	v_lshl_or_b32 v158, s22, 8, v201
	v_ashrrev_i32_e32 v157, 31, v156
	v_lshlrev_b64 v[160:161], 11, v[156:157]
	v_ashrrev_i32_e32 v159, 31, v158
	v_lshl_add_u64 v[160:161], s[54:55], 0, v[160:161]
	v_lshlrev_b64 v[158:159], 1, v[158:159]
	v_lshl_add_u64 v[206:207], v[160:161], 0, v[158:159]
	global_load_dwordx2 v[208:209], v[206:207], off nt
	global_load_dwordx2 v[210:211], v[206:207], off offset:32 nt
	global_load_dwordx2 v[212:213], v[206:207], off offset:256 nt
	global_load_dwordx2 v[214:215], v[206:207], off offset:288 nt
	v_or_b32_e32 v176, 16, v156
	v_or_b32_e32 v164, 32, v156
	v_or_b32_e32 v160, 48, v156
	v_ashrrev_i32_e32 v177, 31, v176
	v_ashrrev_i32_e32 v165, 31, v164
	v_ashrrev_i32_e32 v161, 31, v160
	v_lshlrev_b64 v[162:163], 11, v[176:177]
	v_lshlrev_b64 v[166:167], 11, v[164:165]
	v_lshlrev_b64 v[168:169], 11, v[160:161]
	v_lshl_add_u64 v[162:163], s[54:55], 0, v[162:163]
	v_lshl_add_u64 v[166:167], s[54:55], 0, v[166:167]
	v_lshl_add_u64 v[168:169], s[54:55], 0, v[168:169]
	v_lshl_add_u64 v[186:187], v[162:163], 0, v[158:159]
	v_lshl_add_u64 v[174:175], v[166:167], 0, v[158:159]
	v_lshl_add_u64 v[162:163], v[168:169], 0, v[158:159]
	global_load_dwordx2 v[196:197], v[186:187], off nt
	global_load_dwordx2 v[194:195], v[186:187], off offset:32 nt
	global_load_dwordx2 v[190:191], v[186:187], off offset:256 nt
	global_load_dwordx2 v[188:189], v[186:187], off offset:288 nt
	global_load_dwordx2 v[184:185], v[174:175], off nt
	global_load_dwordx2 v[182:183], v[174:175], off offset:32 nt
	global_load_dwordx2 v[180:181], v[174:175], off offset:256 nt
	global_load_dwordx2 v[178:179], v[174:175], off offset:288 nt
	global_load_dwordx2 v[172:173], v[162:163], off nt
	global_load_dwordx2 v[170:171], v[162:163], off offset:32 nt
	global_load_dwordx2 v[168:169], v[162:163], off offset:256 nt
	global_load_dwordx2 v[166:167], v[162:163], off offset:288 nt
	v_and_b32_e32 v204, 64, v202
	v_xor_b32_e32 v203, 16, v202
	v_add_u32_e32 v204, 64, v204
	v_xor_b32_e32 v205, 32, v202
	v_cmp_lt_i32_e32 vcc, v203, v204
	s_waitcnt vmcnt(0)
	v_lshlrev_b32_e32 v216, 16, v208
	v_cndmask_b32_e32 v203, v202, v203, vcc
	v_cmp_lt_i32_e32 vcc, v205, v204
	v_and_b32_e32 v217, 0xffff0000, v208
	v_lshlrev_b32_e32 v218, 16, v210
	v_and_b32_e32 v219, 0xffff0000, v210
	v_cndmask_b32_e32 v205, v202, v205, vcc
	v_lshlrev_b32_e32 v208, 16, v209
	v_and_b32_e32 v209, 0xffff0000, v209
	v_lshlrev_b32_e32 v220, 16, v212
	v_and_b32_e32 v221, 0xffff0000, v212
	v_lshlrev_b32_e32 v222, 16, v214
	v_and_b32_e32 v223, 0xffff0000, v214
	v_pk_add_f32 v[140:141], v[140:141], v[216:217]
	v_pk_add_f32 v[136:137], v[136:137], v[218:219]
	v_lshlrev_b32_e32 v204, 2, v203
	v_lshlrev_b32_e32 v203, 2, v205
	v_lshlrev_b32_e32 v210, 16, v211
	v_and_b32_e32 v211, 0xffff0000, v211
	v_pk_add_f32 v[142:143], v[142:143], v[208:209]
	v_pk_add_f32 v[132:133], v[132:133], v[220:221]
	v_pk_add_f32 v[208:209], v[128:129], v[222:223]
	v_mul_f32_e32 v205, v141, v141
	v_cvt_pk_bf16_f32 v128, v140, v141
	v_mul_f32_e32 v141, v137, v137
	v_lshlrev_b32_e32 v212, 16, v213
	v_and_b32_e32 v213, 0xffff0000, v213
	v_pk_add_f32 v[138:139], v[138:139], v[210:211]
	v_cvt_pk_bf16_f32 v210, v136, v137
	v_mul_f32_e32 v137, v133, v133
	v_fmac_f32_e32 v205, v140, v140
	v_fmac_f32_e32 v141, v136, v136
	v_lshlrev_b32_e32 v214, 16, v215
	v_and_b32_e32 v215, 0xffff0000, v215
	v_pk_add_f32 v[134:135], v[134:135], v[212:213]
	v_mul_f32_e32 v211, v209, v209
	v_fmac_f32_e32 v137, v132, v132
	v_fmac_f32_e32 v205, v142, v142
	v_fmac_f32_e32 v141, v138, v138
	v_pk_add_f32 v[130:131], v[130:131], v[214:215]
	v_cvt_pk_bf16_f32 v129, v142, v143
	v_fmac_f32_e32 v211, v208, v208
	v_fmac_f32_e32 v137, v134, v134
	v_fmac_f32_e32 v205, v143, v143
	v_fmac_f32_e32 v141, v139, v139
	global_store_dwordx2 v[206:207], v[128:129], off
	v_fmac_f32_e32 v137, v135, v135
	v_add_f32_e32 v128, v205, v141
	v_fmac_f32_e32 v211, v130, v130
	v_add_f32_e32 v128, v128, v137
	v_fmac_f32_e32 v211, v131, v131
	v_add_f32_e32 v128, v128, v211
	ds_bpermute_b32 v129, v204, v128
	v_cvt_pk_bf16_f32 v132, v132, v133
	v_cvt_pk_bf16_f32 v133, v134, v135
	v_cvt_pk_bf16_f32 v211, v138, v139
	global_store_dwordx2 v[206:207], v[132:133], off offset:256
	s_waitcnt lgkmcnt(0)
	v_add_f32_e32 v128, v128, v129
	ds_bpermute_b32 v129, v203, v128
	v_cvt_pk_bf16_f32 v132, v208, v209
	v_cvt_pk_bf16_f32 v133, v130, v131
	global_store_dwordx2 v[206:207], v[210:211], off offset:32
	global_store_dwordx2 v[206:207], v[132:133], off offset:288
	s_and_saveexec_b64 s[20:21], s[4:5]
	s_cbranch_execz .LBB0_1425
	s_waitcnt lgkmcnt(0)
	v_add_f32_e32 v128, v128, v129
	v_fma_f32 v128, v128, s49, 0.5
	v_trunc_f32_e32 v128, v128
	v_mul_f32_e32 v129, 0x2f800000, v128
	v_floor_f32_e32 v129, v129
	v_fmac_f32_e32 v128, 0xcf800000, v129
	v_cvt_u32_f32_e32 v128, v128
	v_cvt_u32_f32_e32 v129, v129
	v_lshl_add_u64 v[130:131], v[156:157], 3, s[8:9]
	global_atomic_add_x2 v[130:131], v[128:129], off

; __device__ __forceinline__ uint2 pack4(f32x4 v) { return make_uint2(pack2(v[0], v[1]), pack2(v[2], v[3])); }
;   __device__ __forceinline__ void operator()(const AccT& acc, const Unit& u, int wr, int wc, int fr, int fq) const {
;     ...
;     for (int ai = 0; ai < 2; ++ai) {
;       f32x4 rv[4][2][2];
; #pragma unroll
;       for (int m = 0; m < 4; ++m) {
;         const size_t ro = (size_t)EPI_ROW(u, ai, m) * DM;
; #pragma unroll
;         for (int bj = 0; bj < 2; ++bj)
; #pragma unroll
;           for (int n = 0; n < 2; ++n) {
;             if (RF32) rv[m][bj][n] = *(const f32x4*)(resid32 + ro + EPI_COL(u, bj, n));
;             else {
;               const uint2 pk = *(const uint2*)(xb + ro + EPI_COL(u, bj, n));
;               rv[m][bj][n] = (f32x4){__uint_as_float(pk.x << 16), __uint_as_float(pk.x & 0xffff0000u), __uint_as_float(pk.y << 16), __uint_as_float(pk.y & 0xffff0000u)};
;             }
;           }
;       }
; #pragma unroll
;       for (int m = 0; m < 4; ++m) {
;         const int row = EPI_ROW(u, ai, m);
;         const size_t ro = (size_t)row * DM;
;         float ss = 0.f;
; #pragma unroll
;         for (int bj = 0; bj < 2; ++bj)
; #pragma unroll
;           for (int n = 0; n < 2; ++n) {
;             const f32x4 x = rv[m][bj][n] + acc[ai][bj][m][n];
;             ss += x[0] * x[0] + x[1] * x[1] + x[2] * x[2] + x[3] * x[3];
;             *(uint2*)(xb + ro + EPI_COL(u, bj, n)) = pack4(x);
;           }
;         ss += __shfl_xor(ss, 16);
;         ss += __shfl_xor(ss, 32);
;         if (fq == 0) atomicAdd(rowss + row, (unsigned long long)(ss * SS_FIX + 0.5f));
;       }
.LBB0_1431:
	s_or_b64 exec, exec, s[20:21]
	v_add_u32_e32 v108, 0x80, v156
	v_ashrrev_i32_e32 v109, 31, v108
	s_waitcnt lgkmcnt(0)
	v_lshlrev_b64 v[80:81], 11, v[108:109]
	v_lshl_add_u64 v[80:81], s[54:55], 0, v[80:81]
	v_lshl_add_u64 v[118:119], v[80:81], 0, v[158:159]
	global_load_dwordx2 v[120:121], v[118:119], off nt
	global_load_dwordx2 v[122:123], v[118:119], off offset:32 nt
	global_load_dwordx2 v[124:125], v[118:119], off offset:256 nt
	global_load_dwordx2 v[126:127], v[118:119], off offset:288 nt
	v_add_u32_e32 v96, 0x90, v156
	v_add_u32_e32 v84, 0xa0, v156
	v_add_u32_e32 v80, 0xb0, v156
	v_ashrrev_i32_e32 v97, 31, v96
	v_ashrrev_i32_e32 v85, 31, v84
	v_ashrrev_i32_e32 v81, 31, v80
	v_lshlrev_b64 v[82:83], 11, v[96:97]
	v_lshlrev_b64 v[86:87], 11, v[84:85]
	v_lshlrev_b64 v[88:89], 11, v[80:81]
	v_lshl_add_u64 v[82:83], s[54:55], 0, v[82:83]
	v_lshl_add_u64 v[86:87], s[54:55], 0, v[86:87]
	v_lshl_add_u64 v[88:89], s[54:55], 0, v[88:89]
	v_lshl_add_u64 v[106:107], v[82:83], 0, v[158:159]
	v_lshl_add_u64 v[94:95], v[86:87], 0, v[158:159]
	v_lshl_add_u64 v[82:83], v[88:89], 0, v[158:159]
	global_load_dwordx2 v[116:117], v[106:107], off nt
	global_load_dwordx2 v[114:115], v[106:107], off offset:32 nt
	global_load_dwordx2 v[112:113], v[106:107], off offset:256 nt
	global_load_dwordx2 v[110:111], v[106:107], off offset:288 nt
	global_load_dwordx2 v[104:105], v[94:95], off nt
	global_load_dwordx2 v[102:103], v[94:95], off offset:32 nt
	global_load_dwordx2 v[100:101], v[94:95], off offset:256 nt
	global_load_dwordx2 v[98:99], v[94:95], off offset:288 nt
	global_load_dwordx2 v[92:93], v[82:83], off nt
	global_load_dwordx2 v[90:91], v[82:83], off offset:32 nt
	global_load_dwordx2 v[88:89], v[82:83], off offset:256 nt
	global_load_dwordx2 v[86:87], v[82:83], off offset:288 nt
	s_waitcnt vmcnt(15)
	v_lshlrev_b32_e32 v128, 16, v120
	v_and_b32_e32 v129, 0xffff0000, v120
	s_waitcnt vmcnt(14)
	v_lshlrev_b32_e32 v130, 16, v122
	v_and_b32_e32 v131, 0xffff0000, v122
	v_lshlrev_b32_e32 v120, 16, v121
	v_and_b32_e32 v121, 0xffff0000, v121
	v_lshlrev_b32_e32 v122, 16, v123
	v_and_b32_e32 v123, 0xffff0000, v123
	s_waitcnt vmcnt(13)
	v_lshlrev_b32_e32 v132, 16, v124
	v_and_b32_e32 v133, 0xffff0000, v124
	s_waitcnt vmcnt(12)
	v_lshlrev_b32_e32 v134, 16, v126
	v_and_b32_e32 v135, 0xffff0000, v126
	v_pk_add_f32 v[76:77], v[76:77], v[128:129]
	v_pk_add_f32 v[72:73], v[72:73], v[130:131]
	v_pk_add_f32 v[78:79], v[78:79], v[120:121]
	v_pk_add_f32 v[74:75], v[74:75], v[122:123]
	v_pk_add_f32 v[68:69], v[68:69], v[132:133]
	v_pk_add_f32 v[120:121], v[64:65], v[134:135]
	v_mul_f32_e32 v123, v77, v77
	v_cvt_pk_bf16_f32 v64, v76, v77
	v_mul_f32_e32 v77, v73, v73
	v_lshlrev_b32_e32 v124, 16, v125
	v_and_b32_e32 v125, 0xffff0000, v125
	v_cvt_pk_bf16_f32 v122, v72, v73
	v_mul_f32_e32 v73, v69, v69
	v_fmac_f32_e32 v123, v76, v76
	v_fmac_f32_e32 v77, v72, v72
	v_lshlrev_b32_e32 v126, 16, v127
	v_and_b32_e32 v127, 0xffff0000, v127
	v_pk_add_f32 v[70:71], v[70:71], v[124:125]
	v_mul_f32_e32 v124, v121, v121
	v_fmac_f32_e32 v73, v68, v68
	v_fmac_f32_e32 v123, v78, v78
	v_fmac_f32_e32 v77, v74, v74
	v_pk_add_f32 v[66:67], v[66:67], v[126:127]
	v_cvt_pk_bf16_f32 v65, v78, v79
	v_fmac_f32_e32 v124, v120, v120
	v_fmac_f32_e32 v73, v70, v70
	v_fmac_f32_e32 v123, v79, v79
	v_fmac_f32_e32 v77, v75, v75
	global_store_dwordx2 v[118:119], v[64:65], off
	v_fmac_f32_e32 v124, v66, v66
	v_fmac_f32_e32 v73, v71, v71
	v_add_f32_e32 v64, v123, v77
	v_add_f32_e32 v64, v64, v73
	v_fmac_f32_e32 v124, v67, v67
	v_add_f32_e32 v64, v64, v124
	ds_bpermute_b32 v65, v204, v64
	v_cvt_pk_bf16_f32 v68, v68, v69
	v_cvt_pk_bf16_f32 v69, v70, v71
	v_cvt_pk_bf16_f32 v123, v74, v75
	global_store_dwordx2 v[118:119], v[68:69], off offset:256
	s_waitcnt lgkmcnt(0)
	v_add_f32_e32 v64, v64, v65
	ds_bpermute_b32 v65, v203, v64
	v_cvt_pk_bf16_f32 v68, v120, v121
	v_cvt_pk_bf16_f32 v69, v66, v67
	global_store_dwordx2 v[118:119], v[122:123], off offset:32
	global_store_dwordx2 v[118:119], v[68:69], off offset:288
	s_and_saveexec_b64 s[20:21], s[4:5]
	s_cbranch_execz .LBB0_1433
	s_waitcnt lgkmcnt(0)
	v_add_f32_e32 v64, v64, v65
	v_fma_f32 v64, v64, s49, 0.5
	v_trunc_f32_e32 v64, v64
	v_mul_f32_e32 v65, 0x2f800000, v64
	v_floor_f32_e32 v65, v65
	v_fmac_f32_e32 v64, 0xcf800000, v65
	v_cvt_u32_f32_e32 v64, v64
	v_cvt_u32_f32_e32 v65, v65
	v_lshl_add_u64 v[66:67], v[108:109], 3, s[8:9]
	global_atomic_add_x2 v[66:67], v[64:65], off

; __device__ __forceinline__ void phase_ffn_fix(const Params& p, int layer) {
;     ...
;   for (int it = blockIdx.x * NTHR + threadIdx.x; it < nitems; it += gridDim.x * NTHR) {
;     const int f4 = it % (DFF / 4), cj = it / (DFF / 4), j = cj & 1, chunk = cj >> 1;
;     const int f0 = f4 * 4;
;     const int gc = 256 * (f0 >> 7) + (f0 & 127);
;     const int t = chunk * 64 + j;
;     const bool has_prev = ((chunk & 63) != 0);
;     const float* cur = p.ub + (size_t)(chunk * 4) * NUP + gc;
;     const float* prv = p.ub + (size_t)((has_prev ? chunk - 1 : chunk) * 4) * NUP + gc;
;     const float pmask = has_prev ? 1.f : 0.f;
;     const float* r1p = (j == 0) ? prv + (size_t)3 * NUP : cur;
;     const float* r2p = (j == 0) ? prv + (size_t)2 * NUP : prv + (size_t)3 * NUP;
;     const float m1 = (j == 0) ? pmask : 1.f, m2 = pmask;
;     f32x4 g0 = *(const f32x4*)(cur + (size_t)j * NUP), v0 = *(const f32x4*)(cur + (size_t)j * NUP + 128);
;     f32x4 g1 = *(const f32x4*)(r1p) * m1, v1 = *(const f32x4*)(r1p + 128) * m1;
;     f32x4 g2 = *(const f32x4*)(r2p) * m2, v2 = *(const f32x4*)(r2p + 128) * m2;
;     const f32x4 wg0 = *(const f32x4*)(cw + f0), wg1 = *(const f32x4*)(cw + NUP + f0), wg2 = *(const f32x4*)(cw + 2 * NUP + f0);
;     const f32x4 wv0 = *(const f32x4*)(cw + DFF + f0), wv1 = *(const f32x4*)(cw + NUP + DFF + f0), wv2 = *(const f32x4*)(cw + 2 * NUP + DFF + f0);
;     const f32x4 bg = *(const f32x4*)(cb + f0), bv = *(const f32x4*)(cb + DFF + f0);
;     const f32x4 cg_ = bg + g2 * wg0 + g1 * wg1 + g0 * wg2;
;     const f32x4 cv_ = bv + v2 * wv0 + v1 * wv1 + v0 * wv2;
;     const float r0 = cg_[0] / (1.f + __expf(-cg_[0])) * cv_[0], r1 = cg_[1] / (1.f + __expf(-cg_[1])) * cv_[1];
;     const float r2 = cg_[2] / (1.f + __expf(-cg_[2])) * cv_[2], r3 = cg_[3] / (1.f + __expf(-cg_[3])) * cv_[3];
;     *(uint2*)(p.act + (size_t)t * DFF + f0) = make_uint2(pack2(r0, r1), pack2(r2, r3));
;   }
.LBB0_1583:
	v_mul_hi_i32 v2, v6, s36
	v_lshrrev_b32_e32 v9, 31, v2
	v_ashrrev_i32_e32 v2, 7, v2
	v_add_u32_e32 v6, s0, v6
	v_add_u32_e32 v2, v2, v9
	v_cmp_lt_i32_e32 vcc, s40, v6
	v_mul_i32_i24_e32 v9, 0x2c0, v2
	v_and_b32_e32 v50, 1, v2
	v_ashrrev_i32_e32 v10, 1, v2
	v_and_b32_e32 v2, 0x7e, v2
	s_or_b64 s[30:31], vcc, s[30:31]
	v_lshlrev_b32_e32 v11, 2, v9
	v_cmp_ne_u32_e32 vcc, 0, v2
	v_lshlrev_b32_e32 v9, 3, v9
	v_lshl_or_b32 v14, v10, 6, v50
	v_lshlrev_b32_e32 v12, 2, v10
	v_subbrev_co_u32_e64 v2, s[4:5], 0, v10, vcc
	v_sub_u32_e32 v10, v7, v11
	v_sub_u32_e32 v9, v8, v9
	v_mul_hi_i32_i24_e32 v13, 0x5800, v12
	v_mul_i32_i24_e32 v12, 0x5800, v12
	v_and_b32_e32 v16, 0x7c, v10
	v_lshl_add_u64 v[42:43], s[56:57], 0, v[12:13]
	v_and_or_b32 v12, v9, s37, v16
	v_lshlrev_b32_e32 v11, 2, v2
	v_ashrrev_i32_e32 v13, 31, v12
	v_mad_i64_i32 v[44:45], s[4:5], v11, s38, v[0:1]
	v_lshlrev_b64 v[46:47], 2, v[12:13]
	v_mul_u32_u24_e32 v15, 0x1600, v50
	v_ashrrev_i32_e32 v11, 31, v10
	v_lshl_add_u64 v[44:45], v[44:45], 0, v[46:47]
	v_cndmask_b32_e64 v66, 0, 1.0, vcc
	v_lshlrev_b32_e32 v2, 2, v15
	v_mad_i64_i32 v[14:15], s[4:5], v14, s39, v[4:5]
	v_lshlrev_b64 v[16:17], 2, v[10:11]
	v_lshl_add_u64 v[42:43], v[42:43], 0, v[46:47]
	v_lshl_add_u64 v[46:47], v[44:45], 0, s[12:13]
	v_lshl_add_u64 v[44:45], v[44:45], 0, s[34:35]
	v_cmp_eq_u32_e32 vcc, 0, v50
	v_lshl_add_u64 v[68:69], v[10:11], 1, v[14:15]
	v_lshl_add_u64 v[10:11], s[14:15], 0, v[16:17]
	v_lshl_add_u64 v[14:15], s[18:19], 0, v[16:17]
	v_lshl_add_u64 v[18:19], s[20:21], 0, v[16:17]
	v_lshl_add_u64 v[22:23], s[22:23], 0, v[16:17]
	v_lshl_add_u64 v[26:27], s[24:25], 0, v[16:17]
	s_waitcnt vmcnt(0)
	v_lshl_add_u64 v[30:31], s[26:27], 0, v[16:17]
	v_lshl_add_u64 v[34:35], s[16:17], 0, v[16:17]
	v_lshl_add_u64 v[38:39], s[28:29], 0, v[16:17]
	v_lshl_add_u64 v[48:49], v[42:43], 0, v[2:3]
	v_cndmask_b32_e32 v55, v43, v47, vcc
	v_cndmask_b32_e32 v54, v42, v46, vcc
	v_cndmask_b32_e32 v63, v47, v45, vcc
	v_cndmask_b32_e32 v62, v46, v44, vcc
	global_load_dwordx4 v[10:13], v[10:11], off nt
	s_nop 0
	global_load_dwordx4 v[14:17], v[14:15], off nt
	s_nop 0
	global_load_dwordx4 v[18:21], v[18:19], off nt
	s_nop 0
	global_load_dwordx4 v[22:25], v[22:23], off nt
	s_nop 0
	global_load_dwordx4 v[26:29], v[26:27], off nt
	s_nop 0
	global_load_dwordx4 v[30:33], v[30:31], off nt
	s_nop 0
	global_load_dwordx4 v[34:37], v[34:35], off nt
	s_nop 0
	global_load_dwordx4 v[38:41], v[38:39], off nt
	s_nop 0
	global_load_dwordx4 v[42:45], v[48:49], off nt
	s_nop 0
	global_load_dwordx4 v[46:49], v[48:49], off offset:512 nt
	s_nop 0
	global_load_dwordx4 v[50:53], v[54:55], off nt
	s_nop 0
	global_load_dwordx4 v[54:57], v[54:55], off offset:512 nt
	s_nop 0
	global_load_dwordx4 v[58:61], v[62:63], off nt
	s_nop 0
	global_load_dwordx4 v[62:65], v[62:63], off offset:512 nt
	v_cndmask_b32_e32 v2, 1.0, v66, vcc
	v_add_u32_e32 v7, s1, v7
	v_add_u32_e32 v8, s3, v8
	s_waitcnt vmcnt(3)
	v_pk_mul_f32 v[50:51], v[50:51], v[2:3] op_sel_hi:[1,0]
	v_pk_mul_f32 v[52:53], v[52:53], v[2:3] op_sel_hi:[1,0]
	s_waitcnt vmcnt(1)
	v_pk_mul_f32 v[58:59], v[58:59], v[66:67] op_sel_hi:[1,0]
	v_pk_mul_f32 v[60:61], v[60:61], v[66:67] op_sel_hi:[1,0]
	v_pk_fma_f32 v[10:11], v[58:59], v[10:11], v[34:35]
	v_pk_fma_f32 v[12:13], v[60:61], v[12:13], v[36:37]
	v_pk_fma_f32 v[10:11], v[50:51], v[14:15], v[10:11]
	v_pk_mul_f32 v[56:57], v[56:57], v[2:3] op_sel_hi:[1,0]
	v_pk_fma_f32 v[10:11], v[42:43], v[18:19], v[10:11]
	v_pk_mul_f32 v[54:55], v[54:55], v[2:3] op_sel_hi:[1,0]
	v_pk_fma_f32 v[12:13], v[52:53], v[16:17], v[12:13]
	v_mul_f32_e32 v2, 0xbfb8aa3b, v10
	v_mul_f32_e32 v9, 0xbfb8aa3b, v11
	v_pk_fma_f32 v[12:13], v[44:45], v[20:21], v[12:13]
	v_exp_f32_e32 v18, v2
	v_exp_f32_e32 v19, v9
	v_mul_f32_e32 v20, 0xbfb8aa3b, v12
	v_mul_f32_e32 v21, 0xbfb8aa3b, v13
	v_exp_f32_e32 v20, v20
	v_exp_f32_e32 v21, v21
	s_waitcnt vmcnt(0)
	v_pk_mul_f32 v[64:65], v[66:67], v[64:65] op_sel_hi:[0,1]
	v_pk_mul_f32 v[62:63], v[66:67], v[62:63] op_sel_hi:[0,1]
	v_pk_add_f32 v[18:19], v[18:19], 1.0 op_sel_hi:[1,0]
	v_pk_fma_f32 v[24:25], v[64:65], v[24:25], v[40:41]
	v_pk_fma_f32 v[22:23], v[62:63], v[22:23], v[38:39]
	v_div_scale_f32 v2, s[4:5], v19, v19, v11
	v_pk_fma_f32 v[14:15], v[56:57], v[28:29], v[24:25]
	v_pk_fma_f32 v[16:17], v[54:55], v[26:27], v[22:23]
	v_pk_add_f32 v[20:21], v[20:21], 1.0 op_sel_hi:[1,0]
	v_div_scale_f32 v22, s[4:5], v18, v18, v10
	v_rcp_f32_e32 v28, v2
	v_div_scale_f32 v24, s[6:7], v21, v21, v13
	v_rcp_f32_e32 v29, v22
	v_pk_fma_f32 v[16:17], v[46:47], v[30:31], v[16:17]
	v_div_scale_f32 v26, s[8:9], v20, v20, v12
	v_rcp_f32_e32 v30, v24
	v_rcp_f32_e32 v31, v26
	v_pk_fma_f32 v[14:15], v[48:49], v[32:33], v[14:15]
	v_fma_f32 v32, -v2, v28, 1.0
	v_div_scale_f32 v9, vcc, v11, v19, v11
	v_fma_f32 v33, -v22, v29, 1.0
	v_fmac_f32_e32 v28, v32, v28
	v_div_scale_f32 v23, s[4:5], v10, v18, v10
	v_fma_f32 v34, -v24, v30, 1.0
	v_fmac_f32_e32 v29, v33, v29
	v_mul_f32_e32 v32, v9, v28
	v_div_scale_f32 v25, s[6:7], v13, v21, v13
	v_fma_f32 v35, -v26, v31, 1.0
	v_fmac_f32_e32 v30, v34, v30
	v_mul_f32_e32 v33, v23, v29
	v_fma_f32 v36, -v2, v32, v9
	v_div_scale_f32 v27, s[8:9], v12, v20, v12
	v_fmac_f32_e32 v31, v35, v31
	v_mul_f32_e32 v34, v25, v30
	v_fma_f32 v37, -v22, v33, v23
	v_fmac_f32_e32 v32, v36, v28
	v_mul_f32_e32 v35, v27, v31
	v_fma_f32 v38, -v24, v34, v25
	v_fmac_f32_e32 v33, v37, v29
	v_fma_f32 v2, -v2, v32, v9
	v_fma_f32 v39, -v26, v35, v27
	v_fmac_f32_e32 v34, v38, v30
	v_fma_f32 v9, -v22, v33, v23
	v_div_fmas_f32 v2, v2, v28, v32
	s_mov_b64 vcc, s[4:5]
	v_fmac_f32_e32 v35, v39, v31
	v_fma_f32 v22, -v24, v34, v25
	v_div_fixup_f32 v11, v2, v19, v11
	v_div_fmas_f32 v2, v9, v29, v33
	s_mov_b64 vcc, s[6:7]
	v_fma_f32 v23, -v26, v35, v27
	v_div_fixup_f32 v10, v2, v18, v10
	v_div_fmas_f32 v2, v22, v30, v34
	s_mov_b64 vcc, s[8:9]
	v_div_fixup_f32 v13, v2, v21, v13
	v_div_fmas_f32 v2, v23, v31, v35
	v_div_fixup_f32 v12, v2, v20, v12
	v_pk_mul_f32 v[10:11], v[16:17], v[10:11]
	v_pk_mul_f32 v[12:13], v[14:15], v[12:13]
	v_cvt_pk_bf16_f32 v10, v10, v11
	v_cvt_pk_bf16_f32 v11, v12, v13
	global_store_dwordx2 v[68:69], v[10:11], off
	s_andn2_b64 exec, exec, s[30:31]
	s_cbranch_execnz .LBB0_1583

; #define PG8_STAGE(bufoff, gbase, voff) do { _Pragma("unroll") for (int _i = 0; _i < 2; ++_i) \
;     __builtin_amdgcn_global_load_lds((const unsigned*)((const char*)(gbase) + (voff)[_i]), (LAS unsigned*)(lds + (bufoff) + ldsw + _i * 8192), 16, 0, 0); } while (0)
; #define PG8_LDB(dst, b, h) do { \
;     PG8_DSR(dst[0][0], baddr, ((b) * 2 + (h)) * PG_HTB + 0 * 2048 + 0);    PG8_DSR(dst[0][1], baddr, ((b) * 2 + (h)) * PG_HTB + 0 * 2048 + 1024); \
;     PG8_DSR(dst[1][0], baddr, ((b) * 2 + (h)) * PG_HTB + 1 * 2048 + 0);    PG8_DSR(dst[1][1], baddr, ((b) * 2 + (h)) * PG_HTB + 1 * 2048 + 1024); } while (0)
; #define PG8_MMA(ai, bj, At, Bt) do { __builtin_amdgcn_s_setprio(1); _Pragma("unroll") for (int m = 0; m < 4; ++m) _Pragma("unroll") for (int n = 0; n < 2; ++n) _Pragma("unroll") for (int k = 0; k < 2; ++k) \
;     acc[ai][bj][m][n] = __builtin_amdgcn_mfma_f32_16x16x32_bf16(Bt[n][k], At[m][k], acc[ai][bj][m][n], 0, 0, 0); __builtin_amdgcn_s_setprio(0); } while (0)
; #define PG8_WAIT_L(n) asm volatile("s_waitcnt lgkmcnt(" #n ")" ::: "memory")
; #define PG8_WAIT_L0 asm volatile("s_waitcnt lgkmcnt(0)" \
;     : "+v"(At[0][0]), "+v"(At[0][1]), "+v"(At[1][0]), "+v"(At[1][1]), "+v"(At[2][0]), "+v"(At[2][1]), "+v"(At[3][0]), "+v"(At[3][1]), \
;       "+v"(B0[0][0]), "+v"(B0[0][1]), "+v"(B0[1][0]), "+v"(B0[1][1]), "+v"(B1[0][0]), "+v"(B1[0][1]), "+v"(B1[1][0]), "+v"(B1[1][1]) :: "memory")
; #define PG8_BAR __builtin_amdgcn_s_barrier()
; template <class Epi>
; __device__ __forceinline__ void gemm_phase(LAS unsigned char* lds, const Gemm g, const StaticOrder& S, const Epi& E) {
;     ...
;     for (int t = 0; t < nt; t += 2) {
;       const bool last = (t == nt - 2);
;       const char* a1 = cA + (size_t)(t + 1) * kstep;
;       const char* a2 = last ? nA : cA + (size_t)(t + 2) * kstep; const char* b2 = last ? nB : cB + (size_t)(t + 2) * kstep;
;       const char* a3 = a2 + kstep; const char* b3 = b2 + kstep;
;       PG8_LDB(B0, 0, 0); PG8_SCHED; PG8_LDA(At, 0, 0); PG8_STAGE(PG8_SA(1, 1), a1 + hstep, voffA);
;       PG8_WAIT_L(8); PG8_BAR; PG8_WAIT_L0; PG8_MMA(0, 0, At, B0); PG8_BAR; PG8_SCHED;
;       PG8_LDB(B1, 0, 1); PG8_STAGE(PG8_SB(0, 0), b2, voffA);
;       PG8_BAR; PG8_WAIT_L0; PG8_MMA(0, 1, At, B1); PG8_BAR;
;       PG8_LDA(At, 0, 1); PG8_STAGE(PG8_SA(0, 0), a2, voffA);
;       PG8_BAR; PG8_WAIT_L0; PG8_MMA(1, 0, At, B0); PG8_BAR; PG8_SCHED;
.LBB0_1649:
	ds_read_b128 v[156:159], v200 offset:0
	ds_read_b128 v[160:163], v200 offset:0x400
	ds_read_b128 v[164:167], v200 offset:0x800
	s_add_u32 s18, s16, 0xfff50080
	ds_read_b128 v[168:171], v200 offset:0xc00
	s_addc_u32 s19, s17, -1
	s_cmp_eq_u32 s49, 40
	s_cselect_b32 s21, s9, s19
	s_cselect_b32 s20, s8, s18
	ds_read_b128 v[172:175], v199 offset:0
	ds_read_b128 v[176:179], v199 offset:0x400
	ds_read_b128 v[180:183], v199 offset:0x800
	ds_read_b128 v[184:187], v199 offset:0xc00
	ds_read_b128 v[188:191], v199 offset:0x1000
	ds_read_b128 v[194:197], v199 offset:0x1400
	ds_read_b128 v[204:207], v199 offset:0x1800
	s_mov_b32 m0, s40
	ds_read_b128 v[208:211], v199 offset:0x1c00
	v_lshl_add_u64 v[212:213], s[16:17], 0, v[148:149]
	global_load_lds_dwordx4 v[212:213], off
	v_lshl_add_u64 v[212:213], s[16:17], 0, v[150:151]
	s_mov_b32 m0, s41
	s_cselect_b32 s19, s11, s48
	global_load_lds_dwordx4 v[212:213], off
	s_waitcnt lgkmcnt(8)
	s_barrier
	s_waitcnt lgkmcnt(0)
	s_cselect_b32 s18, s10, s47
	s_setprio 1
	v_mfma_f32_16x16x32_bf16 v[0:3], v[156:159], v[172:175], v[140:143]
	v_mfma_f32_16x16x32_bf16 v[4:7], v[164:167], v[172:175], v[136:139]
	v_mfma_f32_16x16x32_bf16 v[8:11], v[156:159], v[180:183], v[124:127]
	v_mfma_f32_16x16x32_bf16 v[12:15], v[164:167], v[180:183], v[120:123]
	v_mfma_f32_16x16x32_bf16 v[108:111], v[156:159], v[188:191], v[108:111]
	v_mfma_f32_16x16x32_bf16 v[104:107], v[164:167], v[188:191], v[104:107]
	v_mfma_f32_16x16x32_bf16 v[92:95], v[156:159], v[204:207], v[92:95]
	v_mfma_f32_16x16x32_bf16 v[88:91], v[164:167], v[204:207], v[88:91]
	v_mfma_f32_16x16x32_bf16 v[0:3], v[160:163], v[176:179], v[0:3]
	v_mfma_f32_16x16x32_bf16 v[4:7], v[168:171], v[176:179], v[4:7]
	v_mfma_f32_16x16x32_bf16 v[8:11], v[160:163], v[184:187], v[8:11]
	v_mfma_f32_16x16x32_bf16 v[12:15], v[168:171], v[184:187], v[12:15]
	v_mfma_f32_16x16x32_bf16 v[108:111], v[160:163], v[194:197], v[108:111]
	v_mfma_f32_16x16x32_bf16 v[104:107], v[168:171], v[194:197], v[104:107]
	v_mfma_f32_16x16x32_bf16 v[92:95], v[160:163], v[208:211], v[92:95]
	v_mfma_f32_16x16x32_bf16 v[88:91], v[168:171], v[208:211], v[88:91]
	s_setprio 0
	s_barrier
	ds_read_b128 v[120:123], v200 offset:0x4000
	ds_read_b128 v[124:127], v200 offset:0x4400
	ds_read_b128 v[136:139], v200 offset:0x4800
	s_mov_b32 m0, s22
	ds_read_b128 v[140:143], v200 offset:0x4c00
	v_lshl_add_u64 v[212:213], s[18:19], 0, v[144:145]
	global_load_lds_dwordx4 v[212:213], off
	v_lshl_add_u64 v[214:215], s[18:19], 0, v[146:147]
	s_mov_b32 m0, s23
	s_nop 0
	global_load_lds_dwordx4 v[214:215], off
	s_barrier
	s_waitcnt lgkmcnt(0)
	s_setprio 1
	v_mfma_f32_16x16x32_bf16 v[132:135], v[120:123], v[172:175], v[132:135]
	v_mfma_f32_16x16x32_bf16 v[128:131], v[136:139], v[172:175], v[128:131]
	v_mfma_f32_16x16x32_bf16 v[116:119], v[120:123], v[180:183], v[116:119]
	v_mfma_f32_16x16x32_bf16 v[112:115], v[136:139], v[180:183], v[112:115]
	v_mfma_f32_16x16x32_bf16 v[100:103], v[120:123], v[188:191], v[100:103]
	v_mfma_f32_16x16x32_bf16 v[96:99], v[136:139], v[188:191], v[96:99]
	v_mfma_f32_16x16x32_bf16 v[84:87], v[120:123], v[204:207], v[84:87]
	v_mfma_f32_16x16x32_bf16 v[80:83], v[136:139], v[204:207], v[80:83]
	v_mfma_f32_16x16x32_bf16 v[132:135], v[124:127], v[176:179], v[132:135]
	v_mfma_f32_16x16x32_bf16 v[128:131], v[140:143], v[176:179], v[128:131]
	v_mfma_f32_16x16x32_bf16 v[116:119], v[124:127], v[184:187], v[116:119]
	v_mfma_f32_16x16x32_bf16 v[112:115], v[140:143], v[184:187], v[112:115]
	v_mfma_f32_16x16x32_bf16 v[100:103], v[124:127], v[194:197], v[100:103]
	v_mfma_f32_16x16x32_bf16 v[96:99], v[140:143], v[194:197], v[96:99]
	v_mfma_f32_16x16x32_bf16 v[84:87], v[124:127], v[208:211], v[84:87]
	v_mfma_f32_16x16x32_bf16 v[80:83], v[140:143], v[208:211], v[80:83]
	s_setprio 0
	s_barrier
	ds_read_b128 v[172:175], v199 offset:0x4000
	ds_read_b128 v[176:179], v199 offset:0x4400
	ds_read_b128 v[180:183], v199 offset:0x4800
	ds_read_b128 v[184:187], v199 offset:0x4c00
	ds_read_b128 v[188:191], v199 offset:0x5000
	ds_read_b128 v[194:197], v199 offset:0x5400
	ds_read_b128 v[204:207], v199 offset:0x5800
	s_mov_b32 m0, s3
	ds_read_b128 v[208:211], v199 offset:0x5c00
	v_lshl_add_u64 v[216:217], s[20:21], 0, v[144:145]
	global_load_lds_dwordx4 v[216:217], off
	v_lshl_add_u64 v[218:219], s[20:21], 0, v[146:147]
	s_mov_b32 m0, s24
	s_nop 0
	global_load_lds_dwordx4 v[218:219], off
	s_barrier
	s_waitcnt lgkmcnt(0)
	s_setprio 1
	v_mfma_f32_16x16x32_bf16 v[76:79], v[156:159], v[172:175], v[76:79]
	v_mfma_f32_16x16x32_bf16 v[72:75], v[164:167], v[172:175], v[72:75]
	v_mfma_f32_16x16x32_bf16 v[60:63], v[156:159], v[180:183], v[60:63]
	v_mfma_f32_16x16x32_bf16 v[56:59], v[164:167], v[180:183], v[56:59]
	v_mfma_f32_16x16x32_bf16 v[44:47], v[156:159], v[188:191], v[44:47]
	v_mfma_f32_16x16x32_bf16 v[40:43], v[164:167], v[188:191], v[40:43]
	v_mfma_f32_16x16x32_bf16 v[28:31], v[156:159], v[204:207], v[28:31]
	v_mfma_f32_16x16x32_bf16 v[24:27], v[164:167], v[204:207], v[24:27]
	v_mfma_f32_16x16x32_bf16 v[76:79], v[160:163], v[176:179], v[76:79]
	v_mfma_f32_16x16x32_bf16 v[72:75], v[168:171], v[176:179], v[72:75]
	v_mfma_f32_16x16x32_bf16 v[60:63], v[160:163], v[184:187], v[60:63]
	v_mfma_f32_16x16x32_bf16 v[56:59], v[168:171], v[184:187], v[56:59]
	v_mfma_f32_16x16x32_bf16 v[44:47], v[160:163], v[194:197], v[44:47]
	v_mfma_f32_16x16x32_bf16 v[40:43], v[168:171], v[194:197], v[40:43]
	v_mfma_f32_16x16x32_bf16 v[28:31], v[160:163], v[208:211], v[28:31]
	v_mfma_f32_16x16x32_bf16 v[24:27], v[168:171], v[208:211], v[24:27]
	s_setprio 0
	s_barrier
; #define PG8_STAGE(bufoff, gbase, voff) do { _Pragma("unroll") for (int _i = 0; _i < 2; ++_i) \
;     __builtin_amdgcn_global_load_lds((const unsigned*)((const char*)(gbase) + (voff)[_i]), (LAS unsigned*)(lds + (bufoff) + ldsw + _i * 8192), 16, 0, 0); } while (0)
; #define PG8_LDB(dst, b, h) do { \
;     PG8_DSR(dst[0][0], baddr, ((b) * 2 + (h)) * PG_HTB + 0 * 2048 + 0);    PG8_DSR(dst[0][1], baddr, ((b) * 2 + (h)) * PG_HTB + 0 * 2048 + 1024); \
;     PG8_DSR(dst[1][0], baddr, ((b) * 2 + (h)) * PG_HTB + 1 * 2048 + 0);    PG8_DSR(dst[1][1], baddr, ((b) * 2 + (h)) * PG_HTB + 1 * 2048 + 1024); } while (0)
; #define PG8_MMA(ai, bj, At, Bt) do { __builtin_amdgcn_s_setprio(1); _Pragma("unroll") for (int m = 0; m < 4; ++m) _Pragma("unroll") for (int n = 0; n < 2; ++n) _Pragma("unroll") for (int k = 0; k < 2; ++k) \
;     acc[ai][bj][m][n] = __builtin_amdgcn_mfma_f32_16x16x32_bf16(Bt[n][k], At[m][k], acc[ai][bj][m][n], 0, 0, 0); __builtin_amdgcn_s_setprio(0); } while (0)
; #define PG8_WAIT_V(n) asm volatile("s_waitcnt vmcnt(" #n ")" ::: "memory")
; #define PG8_WAIT_L(n) asm volatile("s_waitcnt lgkmcnt(" #n ")" ::: "memory")
; #define PG8_WAIT_L0 asm volatile("s_waitcnt lgkmcnt(0)" \
;     : "+v"(At[0][0]), "+v"(At[0][1]), "+v"(At[1][0]), "+v"(At[1][1]), "+v"(At[2][0]), "+v"(At[2][1]), "+v"(At[3][0]), "+v"(At[3][1]), \
;       "+v"(B0[0][0]), "+v"(B0[0][1]), "+v"(B0[1][0]), "+v"(B0[1][1]), "+v"(B1[0][0]), "+v"(B1[0][1]), "+v"(B1[1][0]), "+v"(B1[1][1]) :: "memory")
; #define PG8_BAR __builtin_amdgcn_s_barrier()
; #define PG8_SCHED __builtin_amdgcn_sched_barrier(0)
; template <class Epi>
; __device__ __forceinline__ void gemm_phase(LAS unsigned char* lds, const Gemm g, const StaticOrder& S, const Epi& E) {
;     ...
;       PG8_STAGE(PG8_SB(0, 1), b2 + hstep, voffA);
;       PG8_WAIT_V(6); PG8_BAR; PG8_MMA(1, 1, At, B1); PG8_BAR;
;       PG8_LDB(B0, 1, 0); PG8_SCHED; PG8_LDA(At, 1, 0); PG8_STAGE(PG8_SA(0, 1), a2 + hstep, voffA);
;       PG8_WAIT_L(8); PG8_BAR; PG8_WAIT_L0; PG8_MMA(0, 0, At, B0); PG8_BAR; PG8_SCHED;
;       PG8_LDB(B1, 1, 1); PG8_STAGE(PG8_SB(1, 0), b3, voffA);
;       PG8_BAR; PG8_WAIT_L0; PG8_MMA(0, 1, At, B1); PG8_BAR;
;       PG8_LDA(At, 1, 1); PG8_STAGE(PG8_SA(1, 0), a3, voffA);
	s_add_u32 s50, s18, 0xb0000
	s_addc_u32 s51, s19, 0
	s_mov_b32 m0, s25
	v_lshl_add_u64 v[156:157], s[50:51], 0, v[144:145]
	global_load_lds_dwordx4 v[156:157], off
	v_lshl_add_u64 v[156:157], s[50:51], 0, v[146:147]
	s_mov_b32 m0, s26
	s_nop 0
	global_load_lds_dwordx4 v[156:157], off
	s_waitcnt vmcnt(6)
	s_barrier
	s_setprio 1
	v_mfma_f32_16x16x32_bf16 v[68:71], v[120:123], v[172:175], v[68:71]
	v_mfma_f32_16x16x32_bf16 v[64:67], v[136:139], v[172:175], v[64:67]
	v_mfma_f32_16x16x32_bf16 v[52:55], v[120:123], v[180:183], v[52:55]
	v_mfma_f32_16x16x32_bf16 v[48:51], v[136:139], v[180:183], v[48:51]
	v_mfma_f32_16x16x32_bf16 v[36:39], v[120:123], v[188:191], v[36:39]
	v_mfma_f32_16x16x32_bf16 v[32:35], v[136:139], v[188:191], v[32:35]
	v_mfma_f32_16x16x32_bf16 v[20:23], v[120:123], v[204:207], v[20:23]
	v_mfma_f32_16x16x32_bf16 v[16:19], v[136:139], v[204:207], v[16:19]
	v_mfma_f32_16x16x32_bf16 v[68:71], v[124:127], v[176:179], v[68:71]
	v_mfma_f32_16x16x32_bf16 v[64:67], v[140:143], v[176:179], v[64:67]
	v_mfma_f32_16x16x32_bf16 v[52:55], v[124:127], v[184:187], v[52:55]
	v_mfma_f32_16x16x32_bf16 v[48:51], v[140:143], v[184:187], v[48:51]
	v_mfma_f32_16x16x32_bf16 v[36:39], v[124:127], v[194:197], v[36:39]
	v_mfma_f32_16x16x32_bf16 v[32:35], v[140:143], v[194:197], v[32:35]
	v_mfma_f32_16x16x32_bf16 v[20:23], v[124:127], v[208:211], v[20:23]
	v_mfma_f32_16x16x32_bf16 v[16:19], v[140:143], v[208:211], v[16:19]
	s_setprio 0
	s_barrier
	ds_read_b128 v[156:159], v200 offset:0x8000
	ds_read_b128 v[160:163], v200 offset:0x8400
	ds_read_b128 v[164:167], v200 offset:0x8800
	ds_read_b128 v[168:171], v200 offset:0x8c00
	ds_read_b128 v[172:175], v199 offset:0x8000
	ds_read_b128 v[176:179], v199 offset:0x8400
	ds_read_b128 v[180:183], v199 offset:0x8800
	ds_read_b128 v[184:187], v199 offset:0x8c00
	ds_read_b128 v[188:191], v199 offset:0x9000
	ds_read_b128 v[194:197], v199 offset:0x9400
	s_add_u32 s20, s20, 0xb0000
	ds_read_b128 v[204:207], v199 offset:0x9800
	s_addc_u32 s21, s21, 0
	s_mov_b32 m0, s27
	ds_read_b128 v[208:211], v199 offset:0x9c00
	v_lshl_add_u64 v[220:221], s[20:21], 0, v[144:145]
	global_load_lds_dwordx4 v[220:221], off
	v_lshl_add_u64 v[220:221], s[20:21], 0, v[146:147]
	s_mov_b32 m0, s28
	s_nop 0
	global_load_lds_dwordx4 v[220:221], off
	s_waitcnt lgkmcnt(8)
	s_barrier
	s_waitcnt lgkmcnt(0)
	s_setprio 1
	v_mfma_f32_16x16x32_bf16 v[0:3], v[156:159], v[172:175], v[0:3]
	v_mfma_f32_16x16x32_bf16 v[140:143], v[160:163], v[176:179], v[0:3]
	v_mfma_f32_16x16x32_bf16 v[0:3], v[164:167], v[172:175], v[4:7]
	v_mfma_f32_16x16x32_bf16 v[136:139], v[168:171], v[176:179], v[0:3]
	v_mfma_f32_16x16x32_bf16 v[0:3], v[156:159], v[180:183], v[8:11]
	v_mfma_f32_16x16x32_bf16 v[124:127], v[160:163], v[184:187], v[0:3]
	v_mfma_f32_16x16x32_bf16 v[0:3], v[164:167], v[180:183], v[12:15]
	v_mfma_f32_16x16x32_bf16 v[120:123], v[168:171], v[184:187], v[0:3]
	v_mfma_f32_16x16x32_bf16 v[0:3], v[156:159], v[188:191], v[108:111]
	v_mfma_f32_16x16x32_bf16 v[108:111], v[160:163], v[194:197], v[0:3]
	v_mfma_f32_16x16x32_bf16 v[0:3], v[164:167], v[188:191], v[104:107]
	v_mfma_f32_16x16x32_bf16 v[104:107], v[168:171], v[194:197], v[0:3]
	v_mfma_f32_16x16x32_bf16 v[0:3], v[156:159], v[204:207], v[92:95]
	v_mfma_f32_16x16x32_bf16 v[92:95], v[160:163], v[208:211], v[0:3]
	v_mfma_f32_16x16x32_bf16 v[0:3], v[164:167], v[204:207], v[88:91]
	v_mfma_f32_16x16x32_bf16 v[88:91], v[168:171], v[208:211], v[0:3]
	s_setprio 0
	s_barrier
	ds_read_b128 v[12:15], v200 offset:0xc000
	ds_read_b128 v[8:11], v200 offset:0xc400
	ds_read_b128 v[4:7], v200 offset:0xc800
	s_mov_b32 m0, s29
	ds_read_b128 v[0:3], v200 offset:0xcc00
	v_lshl_add_u64 v[212:213], v[212:213], 0, s[14:15]
	global_load_lds_dwordx4 v[212:213], off
	v_lshl_add_u64 v[212:213], v[214:215], 0, s[14:15]
	s_mov_b32 m0, s30
	s_nop 0
	global_load_lds_dwordx4 v[212:213], off
	s_barrier
	s_waitcnt lgkmcnt(0)
	s_setprio 1
	v_mfma_f32_16x16x32_bf16 v[132:135], v[12:15], v[172:175], v[132:135]
	v_mfma_f32_16x16x32_bf16 v[128:131], v[4:7], v[172:175], v[128:131]
	v_mfma_f32_16x16x32_bf16 v[116:119], v[12:15], v[180:183], v[116:119]
	v_mfma_f32_16x16x32_bf16 v[112:115], v[4:7], v[180:183], v[112:115]
	v_mfma_f32_16x16x32_bf16 v[100:103], v[12:15], v[188:191], v[100:103]
	v_mfma_f32_16x16x32_bf16 v[96:99], v[4:7], v[188:191], v[96:99]
	v_mfma_f32_16x16x32_bf16 v[84:87], v[12:15], v[204:207], v[84:87]
	v_mfma_f32_16x16x32_bf16 v[80:83], v[4:7], v[204:207], v[80:83]
	v_mfma_f32_16x16x32_bf16 v[132:135], v[8:11], v[176:179], v[132:135]
	v_mfma_f32_16x16x32_bf16 v[128:131], v[0:3], v[176:179], v[128:131]
	v_mfma_f32_16x16x32_bf16 v[116:119], v[8:11], v[184:187], v[116:119]
	v_mfma_f32_16x16x32_bf16 v[112:115], v[0:3], v[184:187], v[112:115]
	v_mfma_f32_16x16x32_bf16 v[100:103], v[8:11], v[194:197], v[100:103]
	v_mfma_f32_16x16x32_bf16 v[96:99], v[0:3], v[194:197], v[96:99]
	v_mfma_f32_16x16x32_bf16 v[84:87], v[8:11], v[208:211], v[84:87]
	v_mfma_f32_16x16x32_bf16 v[80:83], v[0:3], v[208:211], v[80:83]
	s_setprio 0
	s_barrier
	ds_read_b128 v[172:175], v199 offset:0xc000
	ds_read_b128 v[176:179], v199 offset:0xc400
	ds_read_b128 v[180:183], v199 offset:0xc800
	ds_read_b128 v[184:187], v199 offset:0xcc00
	ds_read_b128 v[188:191], v199 offset:0xd000
	ds_read_b128 v[194:197], v199 offset:0xd400
	ds_read_b128 v[204:207], v199 offset:0xd800
	s_mov_b32 m0, s31
	ds_read_b128 v[208:211], v199 offset:0xdc00
	v_lshl_add_u64 v[212:213], v[216:217], 0, s[14:15]
	global_load_lds_dwordx4 v[212:213], off
	v_lshl_add_u64 v[212:213], v[218:219], 0, s[14:15]
	s_mov_b32 m0, s34
	s_nop 0
	global_load_lds_dwordx4 v[212:213], off
	s_barrier
; #define PG8_STAGE(bufoff, gbase, voff) do { _Pragma("unroll") for (int _i = 0; _i < 2; ++_i) \
;     __builtin_amdgcn_global_load_lds((const unsigned*)((const char*)(gbase) + (voff)[_i]), (LAS unsigned*)(lds + (bufoff) + ldsw + _i * 8192), 16, 0, 0); } while (0)
; #define PG8_MMA(ai, bj, At, Bt) do { __builtin_amdgcn_s_setprio(1); _Pragma("unroll") for (int m = 0; m < 4; ++m) _Pragma("unroll") for (int n = 0; n < 2; ++n) _Pragma("unroll") for (int k = 0; k < 2; ++k) \
;     acc[ai][bj][m][n] = __builtin_amdgcn_mfma_f32_16x16x32_bf16(Bt[n][k], At[m][k], acc[ai][bj][m][n], 0, 0, 0); __builtin_amdgcn_s_setprio(0); } while (0)
; #define PG8_WAIT_V(n) asm volatile("s_waitcnt vmcnt(" #n ")" ::: "memory")
; #define PG8_WAIT_L0 asm volatile("s_waitcnt lgkmcnt(0)" \
;     : "+v"(At[0][0]), "+v"(At[0][1]), "+v"(At[1][0]), "+v"(At[1][1]), "+v"(At[2][0]), "+v"(At[2][1]), "+v"(At[3][0]), "+v"(At[3][1]), \
;       "+v"(B0[0][0]), "+v"(B0[0][1]), "+v"(B0[1][0]), "+v"(B0[1][1]), "+v"(B1[0][0]), "+v"(B1[0][1]), "+v"(B1[1][0]), "+v"(B1[1][1]) :: "memory")
; #define PG8_BAR __builtin_amdgcn_s_barrier()
; #define PG8_SCHED __builtin_amdgcn_sched_barrier(0)
; template <class Epi>
; __device__ __forceinline__ void gemm_phase(LAS unsigned char* lds, const Gemm g, const StaticOrder& S, const Epi& E) {
;     ...
;       PG8_BAR; PG8_WAIT_L0; PG8_MMA(1, 0, At, B0); PG8_BAR; PG8_SCHED;
;       PG8_STAGE(PG8_SB(1, 1), b3 + hstep, voffA);
;       PG8_WAIT_V(6); PG8_BAR; PG8_MMA(1, 1, At, B1); PG8_BAR;
	s_waitcnt lgkmcnt(0)
	s_setprio 1
	v_mfma_f32_16x16x32_bf16 v[76:79], v[156:159], v[172:175], v[76:79]
	v_mfma_f32_16x16x32_bf16 v[72:75], v[164:167], v[172:175], v[72:75]
	v_mfma_f32_16x16x32_bf16 v[60:63], v[156:159], v[180:183], v[60:63]
	v_mfma_f32_16x16x32_bf16 v[56:59], v[164:167], v[180:183], v[56:59]
	v_mfma_f32_16x16x32_bf16 v[44:47], v[156:159], v[188:191], v[44:47]
	v_mfma_f32_16x16x32_bf16 v[40:43], v[164:167], v[188:191], v[40:43]
	v_mfma_f32_16x16x32_bf16 v[28:31], v[156:159], v[204:207], v[28:31]
	v_mfma_f32_16x16x32_bf16 v[24:27], v[164:167], v[204:207], v[24:27]
	v_mfma_f32_16x16x32_bf16 v[76:79], v[160:163], v[176:179], v[76:79]
	v_mfma_f32_16x16x32_bf16 v[72:75], v[168:171], v[176:179], v[72:75]
	v_mfma_f32_16x16x32_bf16 v[60:63], v[160:163], v[184:187], v[60:63]
	v_mfma_f32_16x16x32_bf16 v[56:59], v[168:171], v[184:187], v[56:59]
	v_mfma_f32_16x16x32_bf16 v[44:47], v[160:163], v[194:197], v[44:47]
	v_mfma_f32_16x16x32_bf16 v[40:43], v[168:171], v[194:197], v[40:43]
	v_mfma_f32_16x16x32_bf16 v[28:31], v[160:163], v[208:211], v[28:31]
	v_mfma_f32_16x16x32_bf16 v[24:27], v[168:171], v[208:211], v[24:27]
	s_setprio 0
	s_barrier
	s_add_u32 s18, s18, 0xb0080
	s_addc_u32 s19, s19, 0
	s_mov_b32 m0, s35
	v_lshl_add_u64 v[156:157], s[18:19], 0, v[144:145]
	global_load_lds_dwordx4 v[156:157], off
	v_lshl_add_u64 v[156:157], s[18:19], 0, v[146:147]
	s_mov_b32 m0, s36
	s_nop 0
	global_load_lds_dwordx4 v[156:157], off
	s_waitcnt vmcnt(6)
	s_barrier
	s_setprio 1
	v_mfma_f32_16x16x32_bf16 v[68:71], v[12:15], v[172:175], v[68:71]
	v_mfma_f32_16x16x32_bf16 v[64:67], v[4:7], v[172:175], v[64:67]
	v_mfma_f32_16x16x32_bf16 v[52:55], v[12:15], v[180:183], v[52:55]
	v_mfma_f32_16x16x32_bf16 v[48:51], v[4:7], v[180:183], v[48:51]
	v_mfma_f32_16x16x32_bf16 v[36:39], v[12:15], v[188:191], v[36:39]
	v_mfma_f32_16x16x32_bf16 v[32:35], v[4:7], v[188:191], v[32:35]
	v_mfma_f32_16x16x32_bf16 v[20:23], v[12:15], v[204:207], v[20:23]
	v_mfma_f32_16x16x32_bf16 v[16:19], v[4:7], v[204:207], v[16:19]
	v_mfma_f32_16x16x32_bf16 v[68:71], v[8:11], v[176:179], v[68:71]
	v_mfma_f32_16x16x32_bf16 v[64:67], v[0:3], v[176:179], v[64:67]
	v_mfma_f32_16x16x32_bf16 v[52:55], v[8:11], v[184:187], v[52:55]
	v_mfma_f32_16x16x32_bf16 v[48:51], v[0:3], v[184:187], v[48:51]
	v_mfma_f32_16x16x32_bf16 v[36:39], v[8:11], v[194:197], v[36:39]
	v_mfma_f32_16x16x32_bf16 v[32:35], v[0:3], v[194:197], v[32:35]
	v_mfma_f32_16x16x32_bf16 v[20:23], v[8:11], v[208:211], v[20:23]
	v_mfma_f32_16x16x32_bf16 v[16:19], v[0:3], v[208:211], v[16:19]
	s_setprio 0
	s_add_i32 s49, s49, 2
	s_add_u32 s16, s16, 0x100
	s_addc_u32 s17, s17, 0
	s_add_u32 s47, s47, 0x100
	s_addc_u32 s48, s48, 0
	s_cmp_gt_u32 s49, 41
	s_barrier
	s_cbranch_scc0 .LBB0_1649
; __device__ __forceinline__ uint2 pack4(f32x4 v) { return make_uint2(pack2(v[0], v[1]), pack2(v[2], v[3])); }
;   __device__ __forceinline__ void operator()(const AccT& acc, const Unit& u, int wr, int wc, int fr, int fq) const {
;     ...
;     for (int ai = 0; ai < 2; ++ai) {
;       f32x4 rv[4][2][2];
; #pragma unroll
;       for (int m = 0; m < 4; ++m) {
;         const size_t ro = (size_t)EPI_ROW(u, ai, m) * DM;
; #pragma unroll
;         for (int bj = 0; bj < 2; ++bj)
; #pragma unroll
;           for (int n = 0; n < 2; ++n) {
;             if (RF32) rv[m][bj][n] = *(const f32x4*)(resid32 + ro + EPI_COL(u, bj, n));
;             else {
;               const uint2 pk = *(const uint2*)(xb + ro + EPI_COL(u, bj, n));
;               rv[m][bj][n] = (f32x4){__uint_as_float(pk.x << 16), __uint_as_float(pk.x & 0xffff0000u), __uint_as_float(pk.y << 16), __uint_as_float(pk.y & 0xffff0000u)};
;             }
;           }
;       }
; #pragma unroll
;       for (int m = 0; m < 4; ++m) {
;         const int row = EPI_ROW(u, ai, m);
;         const size_t ro = (size_t)row * DM;
;         float ss = 0.f;
; #pragma unroll
;         for (int bj = 0; bj < 2; ++bj)
; #pragma unroll
;           for (int n = 0; n < 2; ++n) {
;             const f32x4 x = rv[m][bj][n] + acc[ai][bj][m][n];
;             ss += x[0] * x[0] + x[1] * x[1] + x[2] * x[2] + x[3] * x[3];
;             *(uint2*)(xb + ro + EPI_COL(u, bj, n)) = pack4(x);
;           }
;         ss += __shfl_xor(ss, 16);
;         ss += __shfl_xor(ss, 32);
;         if (fq == 0) atomicAdd(rowss + row, (unsigned long long)(ss * SS_FIX + 0.5f));
;       }
	v_lshl_add_u32 v156, s46, 8, v198
	v_lshl_or_b32 v158, s45, 8, v201
	v_ashrrev_i32_e32 v157, 31, v156
	v_lshlrev_b64 v[160:161], 11, v[156:157]
	v_ashrrev_i32_e32 v159, 31, v158
	v_lshl_add_u64 v[160:161], s[54:55], 0, v[160:161]
	v_lshlrev_b64 v[158:159], 1, v[158:159]
	v_lshl_add_u64 v[206:207], v[160:161], 0, v[158:159]
	global_load_dwordx2 v[208:209], v[206:207], off nt
	global_load_dwordx2 v[210:211], v[206:207], off offset:32 nt
	global_load_dwordx2 v[212:213], v[206:207], off offset:256 nt
	global_load_dwordx2 v[214:215], v[206:207], off offset:288 nt
	v_or_b32_e32 v176, 16, v156
	v_or_b32_e32 v164, 32, v156
	v_or_b32_e32 v160, 48, v156
	v_ashrrev_i32_e32 v177, 31, v176
	v_ashrrev_i32_e32 v165, 31, v164
	v_ashrrev_i32_e32 v161, 31, v160
	v_lshlrev_b64 v[162:163], 11, v[176:177]
	v_lshlrev_b64 v[166:167], 11, v[164:165]
	v_lshlrev_b64 v[168:169], 11, v[160:161]
	v_lshl_add_u64 v[162:163], s[54:55], 0, v[162:163]
	v_lshl_add_u64 v[166:167], s[54:55], 0, v[166:167]
	v_lshl_add_u64 v[168:169], s[54:55], 0, v[168:169]
	v_lshl_add_u64 v[186:187], v[162:163], 0, v[158:159]
	v_lshl_add_u64 v[174:175], v[166:167], 0, v[158:159]
	v_lshl_add_u64 v[162:163], v[168:169], 0, v[158:159]
	global_load_dwordx2 v[196:197], v[186:187], off nt
	global_load_dwordx2 v[194:195], v[186:187], off offset:32 nt
	global_load_dwordx2 v[190:191], v[186:187], off offset:256 nt
	global_load_dwordx2 v[188:189], v[186:187], off offset:288 nt
	global_load_dwordx2 v[184:185], v[174:175], off nt
	global_load_dwordx2 v[182:183], v[174:175], off offset:32 nt
	global_load_dwordx2 v[180:181], v[174:175], off offset:256 nt
	global_load_dwordx2 v[178:179], v[174:175], off offset:288 nt
	global_load_dwordx2 v[172:173], v[162:163], off nt
	global_load_dwordx2 v[170:171], v[162:163], off offset:32 nt
	global_load_dwordx2 v[168:169], v[162:163], off offset:256 nt
	global_load_dwordx2 v[166:167], v[162:163], off offset:288 nt
	v_and_b32_e32 v204, 64, v202
	v_xor_b32_e32 v203, 16, v202
	v_add_u32_e32 v204, 64, v204
	v_xor_b32_e32 v205, 32, v202
	v_cmp_lt_i32_e32 vcc, v203, v204
	s_waitcnt vmcnt(0)
	v_lshlrev_b32_e32 v216, 16, v208
	v_cndmask_b32_e32 v203, v202, v203, vcc
	v_cmp_lt_i32_e32 vcc, v205, v204
	v_and_b32_e32 v217, 0xffff0000, v208
	v_lshlrev_b32_e32 v218, 16, v210
	v_and_b32_e32 v219, 0xffff0000, v210
	v_cndmask_b32_e32 v205, v202, v205, vcc
	v_lshlrev_b32_e32 v208, 16, v209
	v_and_b32_e32 v209, 0xffff0000, v209
	v_lshlrev_b32_e32 v220, 16, v212
	v_and_b32_e32 v221, 0xffff0000, v212
	v_lshlrev_b32_e32 v222, 16, v214
	v_and_b32_e32 v223, 0xffff0000, v214
	v_pk_add_f32 v[140:141], v[140:141], v[216:217]
	v_pk_add_f32 v[136:137], v[136:137], v[218:219]
	v_lshlrev_b32_e32 v204, 2, v203
	v_lshlrev_b32_e32 v203, 2, v205
	v_lshlrev_b32_e32 v210, 16, v211
	v_and_b32_e32 v211, 0xffff0000, v211
	v_pk_add_f32 v[142:143], v[142:143], v[208:209]
	v_pk_add_f32 v[132:133], v[132:133], v[220:221]
	v_pk_add_f32 v[208:209], v[128:129], v[222:223]
	v_mul_f32_e32 v205, v141, v141
	v_cvt_pk_bf16_f32 v128, v140, v141
	v_mul_f32_e32 v141, v137, v137
	v_lshlrev_b32_e32 v212, 16, v213
	v_and_b32_e32 v213, 0xffff0000, v213
	v_pk_add_f32 v[138:139], v[138:139], v[210:211]
	v_cvt_pk_bf16_f32 v210, v136, v137
	v_mul_f32_e32 v137, v133, v133
	v_fmac_f32_e32 v205, v140, v140
	v_fmac_f32_e32 v141, v136, v136
	v_lshlrev_b32_e32 v214, 16, v215
	v_and_b32_e32 v215, 0xffff0000, v215
	v_pk_add_f32 v[134:135], v[134:135], v[212:213]
	v_mul_f32_e32 v211, v209, v209
	v_fmac_f32_e32 v137, v132, v132
	v_fmac_f32_e32 v205, v142, v142
	v_fmac_f32_e32 v141, v138, v138
	v_pk_add_f32 v[130:131], v[130:131], v[214:215]
	v_cvt_pk_bf16_f32 v129, v142, v143
	v_fmac_f32_e32 v211, v208, v208
	v_fmac_f32_e32 v137, v134, v134
	v_fmac_f32_e32 v205, v143, v143
	v_fmac_f32_e32 v141, v139, v139
	global_store_dwordx2 v[206:207], v[128:129], off
	v_fmac_f32_e32 v137, v135, v135
	v_add_f32_e32 v128, v205, v141
	v_fmac_f32_e32 v211, v130, v130
	v_add_f32_e32 v128, v128, v137
	v_fmac_f32_e32 v211, v131, v131
	v_add_f32_e32 v128, v128, v211
	ds_bpermute_b32 v129, v204, v128
	v_cvt_pk_bf16_f32 v132, v132, v133
	v_cvt_pk_bf16_f32 v133, v134, v135
	v_cvt_pk_bf16_f32 v211, v138, v139
	global_store_dwordx2 v[206:207], v[132:133], off offset:256
	s_waitcnt lgkmcnt(0)
	v_add_f32_e32 v128, v128, v129
	ds_bpermute_b32 v129, v203, v128
	v_cvt_pk_bf16_f32 v132, v208, v209
	v_cvt_pk_bf16_f32 v133, v130, v131
	global_store_dwordx2 v[206:207], v[210:211], off offset:32
	global_store_dwordx2 v[206:207], v[132:133], off offset:288
	s_and_saveexec_b64 s[16:17], s[4:5]
	s_cbranch_execz .LBB0_1652
	s_waitcnt lgkmcnt(0)
	v_add_f32_e32 v128, v128, v129
	v_fma_f32 v128, v128, s42, 0.5
	v_trunc_f32_e32 v128, v128
	v_mul_f32_e32 v129, 0x2f800000, v128
	v_floor_f32_e32 v129, v129
	v_fmac_f32_e32 v128, 0xcf800000, v129
	v_cvt_u32_f32_e32 v128, v128
	v_cvt_u32_f32_e32 v129, v129
	v_lshl_add_u64 v[130:131], v[156:157], 3, s[12:13]
	global_atomic_add_x2 v[130:131], v[128:129], off

; __device__ __forceinline__ uint2 pack4(f32x4 v) { return make_uint2(pack2(v[0], v[1]), pack2(v[2], v[3])); }
;   __device__ __forceinline__ void operator()(const AccT& acc, const Unit& u, int wr, int wc, int fr, int fq) const {
;     ...
;     for (int ai = 0; ai < 2; ++ai) {
;       f32x4 rv[4][2][2];
; #pragma unroll
;       for (int m = 0; m < 4; ++m) {
;         const size_t ro = (size_t)EPI_ROW(u, ai, m) * DM;
; #pragma unroll
;         for (int bj = 0; bj < 2; ++bj)
; #pragma unroll
;           for (int n = 0; n < 2; ++n) {
;             if (RF32) rv[m][bj][n] = *(const f32x4*)(resid32 + ro + EPI_COL(u, bj, n));
;             else {
;               const uint2 pk = *(const uint2*)(xb + ro + EPI_COL(u, bj, n));
;               rv[m][bj][n] = (f32x4){__uint_as_float(pk.x << 16), __uint_as_float(pk.x & 0xffff0000u), __uint_as_float(pk.y << 16), __uint_as_float(pk.y & 0xffff0000u)};
;             }
;           }
;       }
; #pragma unroll
;       for (int m = 0; m < 4; ++m) {
;         const int row = EPI_ROW(u, ai, m);
;         const size_t ro = (size_t)row * DM;
;         float ss = 0.f;
; #pragma unroll
;         for (int bj = 0; bj < 2; ++bj)
; #pragma unroll
;           for (int n = 0; n < 2; ++n) {
;             const f32x4 x = rv[m][bj][n] + acc[ai][bj][m][n];
;             ss += x[0] * x[0] + x[1] * x[1] + x[2] * x[2] + x[3] * x[3];
;             *(uint2*)(xb + ro + EPI_COL(u, bj, n)) = pack4(x);
;           }
;         ss += __shfl_xor(ss, 16);
;         ss += __shfl_xor(ss, 32);
;         if (fq == 0) atomicAdd(rowss + row, (unsigned long long)(ss * SS_FIX + 0.5f));
;       }
.LBB0_1658:
	s_or_b64 exec, exec, s[16:17]
	v_add_u32_e32 v108, 0x80, v156
	v_ashrrev_i32_e32 v109, 31, v108
	s_waitcnt lgkmcnt(0)
	v_lshlrev_b64 v[80:81], 11, v[108:109]
	v_lshl_add_u64 v[80:81], s[54:55], 0, v[80:81]
	v_lshl_add_u64 v[118:119], v[80:81], 0, v[158:159]
	global_load_dwordx2 v[120:121], v[118:119], off nt
	global_load_dwordx2 v[122:123], v[118:119], off offset:32 nt
	global_load_dwordx2 v[124:125], v[118:119], off offset:256 nt
	global_load_dwordx2 v[126:127], v[118:119], off offset:288 nt
	v_add_u32_e32 v96, 0x90, v156
	v_add_u32_e32 v84, 0xa0, v156
	v_add_u32_e32 v80, 0xb0, v156
	v_ashrrev_i32_e32 v97, 31, v96
	v_ashrrev_i32_e32 v85, 31, v84
	v_ashrrev_i32_e32 v81, 31, v80
	v_lshlrev_b64 v[82:83], 11, v[96:97]
	v_lshlrev_b64 v[86:87], 11, v[84:85]
	v_lshlrev_b64 v[88:89], 11, v[80:81]
	v_lshl_add_u64 v[82:83], s[54:55], 0, v[82:83]
	v_lshl_add_u64 v[86:87], s[54:55], 0, v[86:87]
	v_lshl_add_u64 v[88:89], s[54:55], 0, v[88:89]
	v_lshl_add_u64 v[106:107], v[82:83], 0, v[158:159]
	v_lshl_add_u64 v[94:95], v[86:87], 0, v[158:159]
	v_lshl_add_u64 v[82:83], v[88:89], 0, v[158:159]
	global_load_dwordx2 v[116:117], v[106:107], off nt
	global_load_dwordx2 v[114:115], v[106:107], off offset:32 nt
	global_load_dwordx2 v[112:113], v[106:107], off offset:256 nt
	global_load_dwordx2 v[110:111], v[106:107], off offset:288 nt
	global_load_dwordx2 v[104:105], v[94:95], off nt
	global_load_dwordx2 v[102:103], v[94:95], off offset:32 nt
	global_load_dwordx2 v[100:101], v[94:95], off offset:256 nt
	global_load_dwordx2 v[98:99], v[94:95], off offset:288 nt
	global_load_dwordx2 v[92:93], v[82:83], off nt
	global_load_dwordx2 v[90:91], v[82:83], off offset:32 nt
	global_load_dwordx2 v[88:89], v[82:83], off offset:256 nt
	global_load_dwordx2 v[86:87], v[82:83], off offset:288 nt
	s_waitcnt vmcnt(15)
	v_lshlrev_b32_e32 v128, 16, v120
	v_and_b32_e32 v129, 0xffff0000, v120
	s_waitcnt vmcnt(14)
	v_lshlrev_b32_e32 v130, 16, v122
	v_and_b32_e32 v131, 0xffff0000, v122
	v_lshlrev_b32_e32 v120, 16, v121
	v_and_b32_e32 v121, 0xffff0000, v121
	v_lshlrev_b32_e32 v122, 16, v123
	v_and_b32_e32 v123, 0xffff0000, v123
	s_waitcnt vmcnt(13)
	v_lshlrev_b32_e32 v132, 16, v124
	v_and_b32_e32 v133, 0xffff0000, v124
	s_waitcnt vmcnt(12)
	v_lshlrev_b32_e32 v134, 16, v126
	v_and_b32_e32 v135, 0xffff0000, v126
	v_pk_add_f32 v[76:77], v[76:77], v[128:129]
	v_pk_add_f32 v[72:73], v[72:73], v[130:131]
	v_pk_add_f32 v[78:79], v[78:79], v[120:121]
	v_pk_add_f32 v[74:75], v[74:75], v[122:123]
	v_pk_add_f32 v[68:69], v[68:69], v[132:133]
	v_pk_add_f32 v[120:121], v[64:65], v[134:135]
	v_mul_f32_e32 v123, v77, v77
	v_cvt_pk_bf16_f32 v64, v76, v77
	v_mul_f32_e32 v77, v73, v73
	v_lshlrev_b32_e32 v124, 16, v125
	v_and_b32_e32 v125, 0xffff0000, v125
	v_cvt_pk_bf16_f32 v122, v72, v73
	v_mul_f32_e32 v73, v69, v69
	v_fmac_f32_e32 v123, v76, v76
	v_fmac_f32_e32 v77, v72, v72
	v_lshlrev_b32_e32 v126, 16, v127
	v_and_b32_e32 v127, 0xffff0000, v127
	v_pk_add_f32 v[70:71], v[70:71], v[124:125]
	v_mul_f32_e32 v124, v121, v121
	v_fmac_f32_e32 v73, v68, v68
	v_fmac_f32_e32 v123, v78, v78
	v_fmac_f32_e32 v77, v74, v74
	v_pk_add_f32 v[66:67], v[66:67], v[126:127]
	v_cvt_pk_bf16_f32 v65, v78, v79
	v_fmac_f32_e32 v124, v120, v120
	v_fmac_f32_e32 v73, v70, v70
	v_fmac_f32_e32 v123, v79, v79
	v_fmac_f32_e32 v77, v75, v75
	global_store_dwordx2 v[118:119], v[64:65], off
	v_fmac_f32_e32 v124, v66, v66
	v_fmac_f32_e32 v73, v71, v71
	v_add_f32_e32 v64, v123, v77
	v_add_f32_e32 v64, v64, v73
	v_fmac_f32_e32 v124, v67, v67
	v_add_f32_e32 v64, v64, v124
	ds_bpermute_b32 v65, v204, v64
	v_cvt_pk_bf16_f32 v68, v68, v69
	v_cvt_pk_bf16_f32 v69, v70, v71
	v_cvt_pk_bf16_f32 v123, v74, v75
	global_store_dwordx2 v[118:119], v[68:69], off offset:256
	s_waitcnt lgkmcnt(0)
	v_add_f32_e32 v64, v64, v65
	ds_bpermute_b32 v65, v203, v64
	v_cvt_pk_bf16_f32 v68, v120, v121
	v_cvt_pk_bf16_f32 v69, v66, v67
	global_store_dwordx2 v[118:119], v[122:123], off offset:32
	global_store_dwordx2 v[118:119], v[68:69], off offset:288
	s_and_saveexec_b64 s[16:17], s[4:5]
	s_cbranch_execz .LBB0_1660
	s_waitcnt lgkmcnt(0)
	v_add_f32_e32 v64, v64, v65
	v_fma_f32 v64, v64, s42, 0.5
	v_trunc_f32_e32 v64, v64
	v_mul_f32_e32 v65, 0x2f800000, v64
	v_floor_f32_e32 v65, v65
	v_fmac_f32_e32 v64, 0xcf800000, v65
	v_cvt_u32_f32_e32 v64, v64
	v_cvt_u32_f32_e32 v65, v65
	v_lshl_add_u64 v[66:67], v[108:109], 3, s[12:13]
	global_atomic_add_x2 v[66:67], v[64:65], off

; __device__ __forceinline__ void phase_final_scale(const Params& p) {
;     ...
;   for (int it = blockIdx.x * NTHR + threadIdx.x; it < NTOK * (DM / 8); it += gridDim.x * NTHR) {
;     const int row = it >> 7, c8 = (it & 127) * 8;
;     const uint4 pk = *(const uint4*)(p.xb + (size_t)row * DM + c8);
;     const float rs = rsqrtf((float)rs3[row] * (1.f / (SS_FIX * DM)) + 1e-6f);
;     const float4 g0 = *(const float4*)(p.norm_final + c8), g1 = *(const float4*)(p.norm_final + c8 + 4);
;     float4 o0, o1;
;     o0.x = __uint_as_float(pk.x << 16) * rs * g0.x; o0.y = __uint_as_float(pk.x & 0xffff0000u) * rs * g0.y;
;     o0.z = __uint_as_float(pk.y << 16) * rs * g0.z; o0.w = __uint_as_float(pk.y & 0xffff0000u) * rs * g0.w;
;     o1.x = __uint_as_float(pk.z << 16) * rs * g1.x; o1.y = __uint_as_float(pk.z & 0xffff0000u) * rs * g1.y;
;     o1.z = __uint_as_float(pk.w << 16) * rs * g1.z; o1.w = __uint_as_float(pk.w & 0xffff0000u) * rs * g1.w;
;     __builtin_nontemporal_store((f32x4){o0.x, o0.y, o0.z, o0.w}, (f32x4*)(p.out + (size_t)row * DM + c8));
;     __builtin_nontemporal_store((f32x4){o1.x, o1.y, o1.z, o1.w}, (f32x4*)(p.out + (size_t)row * DM + c8 + 4));
;   }
.LBB0_1720:
	v_ashrrev_i32_e32 v16, 7, v193
	v_ashrrev_i32_e32 v17, 31, v16
	v_and_b32_e32 v12, 0x3f8, v2
	v_lshlrev_b64 v[4:5], 11, v[16:17]
	v_lshlrev_b32_e32 v0, 1, v12
	v_lshl_add_u64 v[8:9], v[16:17], 3, s[0:1]
	v_lshl_add_u64 v[4:5], s[54:55], 0, v[4:5]
	v_lshl_add_u64 v[10:11], v[4:5], 0, v[0:1]
	global_load_dwordx2 v[18:19], v[8:9], off nt
	global_load_dwordx4 v[4:7], v[10:11], off nt
	v_lshlrev_b32_e32 v0, 2, v12
	global_load_dwordx4 v[8:11], v0, s[20:21]
	global_load_dwordx4 v[12:15], v0, s[20:21] offset:16
	v_lshlrev_b64 v[16:17], 12, v[16:17]
	v_lshl_add_u64 v[16:17], s[22:23], 0, v[16:17]
	v_lshl_add_u64 v[16:17], v[16:17], 0, v[0:1]
	v_add_u32_e32 v193, s6, v193
	v_cmp_lt_i32_e32 vcc, s9, v193
	s_or_b64 s[2:3], vcc, s[2:3]
	v_add_u32_e32 v2, s7, v2
	s_waitcnt vmcnt(0)
	v_ffbh_u32_e32 v0, v19
	v_min_u32_e32 v0, 32, v0
	v_lshlrev_b64 v[18:19], v0, v[18:19]
	v_min_u32_e32 v18, 1, v18
	v_or_b32_e32 v18, v19, v18
	v_cvt_f32_u32_e32 v18, v18
	v_sub_u32_e32 v0, 32, v0
	v_lshlrev_b32_e32 v20, 16, v4
	v_and_b32_e32 v21, 0xffff0000, v4
	v_ldexp_f32 v0, v18, v0
	v_fmamk_f32 v0, v0, 0x2e800000, v3
	v_mul_f32_e32 v18, 0x4b800000, v0
	v_cmp_gt_f32_e32 vcc, s8, v0
	v_lshlrev_b32_e32 v4, 16, v5
	v_and_b32_e32 v5, 0xffff0000, v5
	v_cndmask_b32_e32 v0, v0, v18, vcc
	v_rsq_f32_e32 v0, v0
	v_lshlrev_b32_e32 v22, 16, v6
	v_and_b32_e32 v23, 0xffff0000, v6
	v_lshlrev_b32_e32 v6, 16, v7
	v_mul_f32_e32 v18, 0x45800000, v0
	v_cndmask_b32_e32 v0, v0, v18, vcc
	v_and_b32_e32 v7, 0xffff0000, v7
	v_pk_mul_f32 v[18:19], v[0:1], v[20:21] op_sel_hi:[0,1]
	v_pk_mul_f32 v[4:5], v[0:1], v[4:5] op_sel_hi:[0,1]
	v_pk_mul_f32 v[20:21], v[0:1], v[22:23] op_sel_hi:[0,1]
	v_pk_mul_f32 v[22:23], v[0:1], v[6:7] op_sel_hi:[0,1]
	v_pk_mul_f32 v[6:7], v[10:11], v[4:5]
	v_pk_mul_f32 v[4:5], v[8:9], v[18:19]
	v_pk_mul_f32 v[10:11], v[14:15], v[22:23]
	v_pk_mul_f32 v[8:9], v[12:13], v[20:21]
	global_store_dwordx4 v[16:17], v[4:7], off nt
	global_store_dwordx4 v[16:17], v[8:11], off offset:16 nt
	s_andn2_b64 exec, exec, s[2:3]
	s_cbranch_execnz .LBB0_1720
